# GEMM K-loops: in the 6-DMA load segments the global->LDS loads are issued before the 8 LDS fragment reads
# speedup vs baseline: 1.0010x; 1.0010x over previous
; #define PG8_STAGE(bufoff, gbase, voff) do { _Pragma("unroll") for (int _i = 0; _i < 2; ++_i) \
;         __builtin_amdgcn_global_load_lds((const unsigned*)((const char*)(gbase) + (voff)[_i]), (PG8_LAS unsigned*)(lds + (bufoff) + ldsw + _i * 8192), 16, 0, 0); } while (0)
; #define PG8_LDA(dst, b, h) do { _Pragma("unroll") for (int m = 0; m < 4; ++m) _Pragma("unroll") for (int k = 0; k < 2; ++k) dst[m][k] = *(const PG8_LAS bf16x8*)(lds + PG8_SA(b, h) + aoff + m * 2048 + k * 1024); } while (0)
; #define PG8_LDB(dst, b, h) do { _Pragma("unroll") for (int n = 0; n < 2; ++n) _Pragma("unroll") for (int k = 0; k < 2; ++k) dst[n][k] = *(const PG8_LAS bf16x8*)(lds + PG8_SB(b, h) + boff + n * 2048 + k * 1024); } while (0)
; #define PG8_MMA(ai, bj, At, Bt) do { __builtin_amdgcn_s_setprio(1); _Pragma("unroll") for (int m = 0; m < 4; ++m) _Pragma("unroll") for (int n = 0; n < 2; ++n) _Pragma("unroll") for (int k = 0; k < 2; ++k) \
;         acc[ai][bj][m][n] = __builtin_amdgcn_mfma_f32_16x16x32_bf16(Bt[n][k], At[m][k], acc[ai][bj][m][n], 0, 0, 0); __builtin_amdgcn_s_setprio(0); } while (0)
; #define PG8_WAIT_V(n) asm volatile("s_waitcnt vmcnt(" #n ")" ::: "memory")
; #define PG8_WAIT_L(n) asm volatile("s_waitcnt lgkmcnt(" #n ")" ::: "memory")
; #define PG8_BAR __builtin_amdgcn_s_barrier()
; template <class Epi, class Sched, bool ALIGN_EPI = false, bool SP2 = false>
; __device__ __forceinline__ void gemm_phase(PG8_LAS unsigned char* lds, const Gemm g, const Sched& S, const Epi& E) {
;     ...
;             const char* a1 = cA + (size_t)(t + 1) * kstep;
;             const char* a2 = last ? nA : cA + (size_t)(t + 2) * kstep; const char* b2 = last ? nB : cB + (size_t)(t + 2) * kstep;
;             const char* a3 = a2 + kstep; const char* b3 = b2 + kstep;
;             if (last && has_next) S.a_ready(nxt);
;             if constexpr (SP2) {
;             PG8_LDB(B0, 0, 0); PG8_LDB(B1, 0, 1); PG8_SCHED; PG8_LDA(At, 0, 0); PG8_STAGE(PG8_SA(1, 1), a1 + hstep, voffA);
;             PG8_WAIT_V(8); PG8_WAIT_L(0); PG8_BAR; PG8_MMA(0, 0, At, B0); PG8_MMA(0, 1, At, B1); PG8_BAR; PG8_SCHED;
;             PG8_LDA(At, 0, 1); PG8_STAGE(PG8_SB(0, 0), b2, voffB); PG8_STAGE(PG8_SB(0, 1), b2 + hstep, voffB); PG8_STAGE(PG8_SA(0, 0), a2, voffA);
;             PG8_WAIT_V(8); PG8_WAIT_L(0); PG8_BAR; PG8_MMA(1, 0, At, B0); PG8_MMA(1, 1, At, B1); PG8_BAR; PG8_SCHED;
.Lprio_done_86:
.LBB0_86:
	s_add_u32 s26, s38, 0xfff80080
	s_addc_u32 s27, s39, -1
	s_add_i32 s55, 0, 0x10000
	s_cmp_eq_u32 s54, 28
	s_cselect_b32 s27, s29, s27
	s_cselect_b32 s26, s50, s26
	v_add_u32_e32 v142, s55, v147
	s_cselect_b32 s41, s19, s53
	s_cselect_b32 s40, s51, s52
	s_add_i32 s58, 0, 0x14000
	ds_read_b128 v[148:151], v142
	ds_read_b128 v[156:159], v142 offset:1024
	ds_read_b128 v[160:163], v142 offset:2048
	ds_read_b128 v[164:167], v142 offset:3072
	v_add_u32_e32 v142, s58, v147
	ds_read_b128 v[168:171], v142
	ds_read_b128 v[184:187], v142 offset:1024
	ds_read_b128 v[188:191], v142 offset:2048
	ds_read_b128 v[192:195], v142 offset:3072
	v_lshl_add_u64 v[144:145], s[38:39], 0, v[140:141]
	s_add_i32 m0, s25, 0xc000
	ds_read_b128 v[196:199], v155
	ds_read_b128 v[200:203], v155 offset:1024
	ds_read_b128 v[204:207], v155 offset:2048
	ds_read_b128 v[208:211], v155 offset:3072
	ds_read_b128 v[212:215], v155 offset:4096
	ds_read_b128 v[216:219], v155 offset:5120
	ds_read_b128 v[220:223], v155 offset:6144
	ds_read_b128 v[224:227], v155 offset:7168
	global_load_lds_dwordx4 v[144:145], off
	v_lshl_add_u64 v[144:145], s[38:39], 0, v[138:139]
	s_add_i32 m0, s25, 0xe000
	s_nop 0
	global_load_lds_dwordx4 v[144:145], off
	s_waitcnt vmcnt(8)
	s_waitcnt lgkmcnt(0)
	s_barrier
	s_waitcnt lgkmcnt(0)
	v_mfma_f32_16x16x32_bf16 v[128:131], v[148:151], v[196:199], v[128:131]
	v_mfma_f32_16x16x32_bf16 v[124:127], v[160:163], v[196:199], v[124:127]
	v_mfma_f32_16x16x32_bf16 v[112:115], v[148:151], v[204:207], v[112:115]
	v_mfma_f32_16x16x32_bf16 v[108:111], v[160:163], v[204:207], v[108:111]
	v_mfma_f32_16x16x32_bf16 v[96:99], v[148:151], v[212:215], v[96:99]
	v_mfma_f32_16x16x32_bf16 v[92:95], v[160:163], v[212:215], v[92:95]
	v_mfma_f32_16x16x32_bf16 v[80:83], v[148:151], v[220:223], v[80:83]
	v_mfma_f32_16x16x32_bf16 v[76:79], v[160:163], v[220:223], v[76:79]
	v_mfma_f32_16x16x32_bf16 v[128:131], v[156:159], v[200:203], v[128:131]
	v_mfma_f32_16x16x32_bf16 v[124:127], v[164:167], v[200:203], v[124:127]
	v_mfma_f32_16x16x32_bf16 v[112:115], v[156:159], v[208:211], v[112:115]
	v_mfma_f32_16x16x32_bf16 v[108:111], v[164:167], v[208:211], v[108:111]
	v_mfma_f32_16x16x32_bf16 v[96:99], v[156:159], v[216:219], v[96:99]
	v_mfma_f32_16x16x32_bf16 v[92:95], v[164:167], v[216:219], v[92:95]
	v_mfma_f32_16x16x32_bf16 v[80:83], v[156:159], v[224:227], v[80:83]
	v_mfma_f32_16x16x32_bf16 v[76:79], v[164:167], v[224:227], v[76:79]
	v_mfma_f32_16x16x32_bf16 v[120:123], v[168:171], v[196:199], v[120:123]
	v_mfma_f32_16x16x32_bf16 v[116:119], v[188:191], v[196:199], v[116:119]
	v_mfma_f32_16x16x32_bf16 v[104:107], v[168:171], v[204:207], v[104:107]
	v_mfma_f32_16x16x32_bf16 v[100:103], v[188:191], v[204:207], v[100:103]
	v_mfma_f32_16x16x32_bf16 v[88:91], v[168:171], v[212:215], v[88:91]
	v_mfma_f32_16x16x32_bf16 v[84:87], v[188:191], v[212:215], v[84:87]
	v_mfma_f32_16x16x32_bf16 v[72:75], v[168:171], v[220:223], v[72:75]
	v_mfma_f32_16x16x32_bf16 v[68:71], v[188:191], v[220:223], v[68:71]
	v_mfma_f32_16x16x32_bf16 v[120:123], v[184:187], v[200:203], v[120:123]
	v_mfma_f32_16x16x32_bf16 v[116:119], v[192:195], v[200:203], v[116:119]
	v_mfma_f32_16x16x32_bf16 v[104:107], v[184:187], v[208:211], v[104:107]
	v_mfma_f32_16x16x32_bf16 v[100:103], v[192:195], v[208:211], v[100:103]
	v_mfma_f32_16x16x32_bf16 v[88:91], v[184:187], v[216:219], v[88:91]
	v_mfma_f32_16x16x32_bf16 v[84:87], v[192:195], v[216:219], v[84:87]
	v_mfma_f32_16x16x32_bf16 v[72:75], v[184:187], v[224:227], v[72:75]
	v_mfma_f32_16x16x32_bf16 v[68:71], v[192:195], v[224:227], v[68:71]
	s_barrier
	s_add_i32 s55, s55, s24
	v_lshl_add_u64 v[144:145], s[40:41], 0, v[174:175]
	s_mov_b32 m0, s55
	global_load_lds_dwordx4 v[144:145], off
	s_add_i32 m0, s55, 0x2000
	s_add_u32 s56, s40, 0x80000
	v_lshl_add_u64 v[228:229], s[40:41], 0, v[132:133]
	s_addc_u32 s57, s41, 0
	s_add_i32 s55, s58, s24
	global_load_lds_dwordx4 v[228:229], off
	v_lshl_add_u64 v[230:231], s[56:57], 0, v[174:175]
	s_mov_b32 m0, s55
	v_lshl_add_u64 v[232:233], s[26:27], 0, v[134:135]
	global_load_lds_dwordx4 v[230:231], off
	v_lshl_add_u64 v[230:231], s[56:57], 0, v[132:133]
	s_add_i32 m0, s55, 0x2000
	s_nop 0
	global_load_lds_dwordx4 v[230:231], off
	v_lshl_add_u64 v[230:231], s[26:27], 0, v[136:137]
	s_mov_b32 m0, s25
	s_nop 0
	global_load_lds_dwordx4 v[230:231], off
	s_mov_b32 m0, s42
	s_nop 0
	global_load_lds_dwordx4 v[232:233], off
	ds_read_b128 v[196:199], v155 offset:16384
	ds_read_b128 v[200:203], v155 offset:17408
	ds_read_b128 v[204:207], v155 offset:18432
	ds_read_b128 v[208:211], v155 offset:19456
	ds_read_b128 v[212:215], v155 offset:20480
	ds_read_b128 v[216:219], v155 offset:21504
	ds_read_b128 v[220:223], v155 offset:22528
	ds_read_b128 v[224:227], v155 offset:23552
	s_waitcnt vmcnt(8)
	s_waitcnt lgkmcnt(0)
	s_barrier
; #define PG8_STAGE(bufoff, gbase, voff) do { _Pragma("unroll") for (int _i = 0; _i < 2; ++_i) \
;         __builtin_amdgcn_global_load_lds((const unsigned*)((const char*)(gbase) + (voff)[_i]), (PG8_LAS unsigned*)(lds + (bufoff) + ldsw + _i * 8192), 16, 0, 0); } while (0)
; #define PG8_LDA(dst, b, h) do { _Pragma("unroll") for (int m = 0; m < 4; ++m) _Pragma("unroll") for (int k = 0; k < 2; ++k) dst[m][k] = *(const PG8_LAS bf16x8*)(lds + PG8_SA(b, h) + aoff + m * 2048 + k * 1024); } while (0)
; #define PG8_LDB(dst, b, h) do { _Pragma("unroll") for (int n = 0; n < 2; ++n) _Pragma("unroll") for (int k = 0; k < 2; ++k) dst[n][k] = *(const PG8_LAS bf16x8*)(lds + PG8_SB(b, h) + boff + n * 2048 + k * 1024); } while (0)
; #define PG8_MMA(ai, bj, At, Bt) do { __builtin_amdgcn_s_setprio(1); _Pragma("unroll") for (int m = 0; m < 4; ++m) _Pragma("unroll") for (int n = 0; n < 2; ++n) _Pragma("unroll") for (int k = 0; k < 2; ++k) \
;         acc[ai][bj][m][n] = __builtin_amdgcn_mfma_f32_16x16x32_bf16(Bt[n][k], At[m][k], acc[ai][bj][m][n], 0, 0, 0); __builtin_amdgcn_s_setprio(0); } while (0)
; #define PG8_WAIT_V(n) asm volatile("s_waitcnt vmcnt(" #n ")" ::: "memory")
; #define PG8_WAIT_L(n) asm volatile("s_waitcnt lgkmcnt(" #n ")" ::: "memory")
; #define PG8_BAR __builtin_amdgcn_s_barrier()
; #define PG8_SCHED __builtin_amdgcn_sched_barrier(0)
; template <class Epi, class Sched, bool ALIGN_EPI = false, bool SP2 = false>
; __device__ __forceinline__ void gemm_phase(PG8_LAS unsigned char* lds, const Gemm g, const Sched& S, const Epi& E) {
;     ...
;             PG8_LDA(At, 0, 1); PG8_STAGE(PG8_SB(0, 0), b2, voffB); PG8_STAGE(PG8_SB(0, 1), b2 + hstep, voffB); PG8_STAGE(PG8_SA(0, 0), a2, voffA);
;             PG8_WAIT_V(8); PG8_WAIT_L(0); PG8_BAR; PG8_MMA(1, 0, At, B0); PG8_MMA(1, 1, At, B1); PG8_BAR; PG8_SCHED;
;             PG8_LDB(B0, 1, 0); PG8_LDB(B1, 1, 1); PG8_SCHED; PG8_LDA(At, 1, 0); PG8_STAGE(PG8_SA(0, 1), a2 + hstep, voffA);
;             PG8_WAIT_V(8); PG8_WAIT_L(0); PG8_BAR; PG8_MMA(0, 0, At, B0); PG8_MMA(0, 1, At, B1); PG8_BAR; PG8_SCHED;
	s_waitcnt lgkmcnt(0)
	v_mfma_f32_16x16x32_bf16 v[64:67], v[148:151], v[196:199], v[64:67]
	v_mfma_f32_16x16x32_bf16 v[60:63], v[160:163], v[196:199], v[60:63]
	v_mfma_f32_16x16x32_bf16 v[52:55], v[148:151], v[204:207], v[52:55]
	v_mfma_f32_16x16x32_bf16 v[44:47], v[160:163], v[204:207], v[44:47]
	v_mfma_f32_16x16x32_bf16 v[36:39], v[148:151], v[212:215], v[36:39]
	v_mfma_f32_16x16x32_bf16 v[28:31], v[160:163], v[212:215], v[28:31]
	v_mfma_f32_16x16x32_bf16 v[20:23], v[148:151], v[220:223], v[20:23]
	v_mfma_f32_16x16x32_bf16 v[12:15], v[160:163], v[220:223], v[12:15]
	v_mfma_f32_16x16x32_bf16 v[64:67], v[156:159], v[200:203], v[64:67]
	v_mfma_f32_16x16x32_bf16 v[60:63], v[164:167], v[200:203], v[60:63]
	v_mfma_f32_16x16x32_bf16 v[52:55], v[156:159], v[208:211], v[52:55]
	v_mfma_f32_16x16x32_bf16 v[44:47], v[164:167], v[208:211], v[44:47]
	v_mfma_f32_16x16x32_bf16 v[36:39], v[156:159], v[216:219], v[36:39]
	v_mfma_f32_16x16x32_bf16 v[28:31], v[164:167], v[216:219], v[28:31]
	v_mfma_f32_16x16x32_bf16 v[20:23], v[156:159], v[224:227], v[20:23]
	v_mfma_f32_16x16x32_bf16 v[12:15], v[164:167], v[224:227], v[12:15]
	v_mfma_f32_16x16x32_bf16 v[56:59], v[168:171], v[196:199], v[56:59]
	v_mfma_f32_16x16x32_bf16 v[48:51], v[188:191], v[196:199], v[48:51]
	v_mfma_f32_16x16x32_bf16 v[40:43], v[168:171], v[204:207], v[40:43]
	v_mfma_f32_16x16x32_bf16 v[32:35], v[188:191], v[204:207], v[32:35]
	v_mfma_f32_16x16x32_bf16 v[24:27], v[168:171], v[212:215], v[24:27]
	v_mfma_f32_16x16x32_bf16 v[16:19], v[188:191], v[212:215], v[16:19]
	v_mfma_f32_16x16x32_bf16 v[8:11], v[168:171], v[220:223], v[8:11]
	v_mfma_f32_16x16x32_bf16 v[4:7], v[188:191], v[220:223], v[4:7]
	v_mfma_f32_16x16x32_bf16 v[56:59], v[184:187], v[200:203], v[56:59]
	v_mfma_f32_16x16x32_bf16 v[48:51], v[192:195], v[200:203], v[48:51]
	v_mfma_f32_16x16x32_bf16 v[40:43], v[184:187], v[208:211], v[40:43]
	v_mfma_f32_16x16x32_bf16 v[32:35], v[192:195], v[208:211], v[32:35]
	v_mfma_f32_16x16x32_bf16 v[24:27], v[184:187], v[216:219], v[24:27]
	v_mfma_f32_16x16x32_bf16 v[16:19], v[192:195], v[216:219], v[16:19]
	v_mfma_f32_16x16x32_bf16 v[8:11], v[184:187], v[224:227], v[8:11]
	v_mfma_f32_16x16x32_bf16 v[4:7], v[192:195], v[224:227], v[4:7]
	s_barrier
	s_add_i32 s55, 0, 0x18000
	v_add_u32_e32 v142, s55, v147
	s_add_i32 s56, 0, 0x1c000
	ds_read_b128 v[148:151], v142
	ds_read_b128 v[156:159], v142 offset:1024
	ds_read_b128 v[160:163], v142 offset:2048
	ds_read_b128 v[164:167], v142 offset:3072
	v_add_u32_e32 v142, s56, v147
	ds_read_b128 v[168:171], v142
	ds_read_b128 v[184:187], v142 offset:1024
	ds_read_b128 v[188:191], v142 offset:2048
	ds_read_b128 v[192:195], v142 offset:3072
	s_add_u32 s26, s26, 0x80000
	s_addc_u32 s27, s27, 0
	s_mov_b32 m0, s43
	v_lshl_add_u64 v[234:235], s[26:27], 0, v[136:137]
	ds_read_b128 v[196:199], v155 offset:32768
	ds_read_b128 v[200:203], v155 offset:33792
	ds_read_b128 v[204:207], v155 offset:34816
	ds_read_b128 v[208:211], v155 offset:35840
	ds_read_b128 v[212:215], v155 offset:36864
	ds_read_b128 v[216:219], v155 offset:37888
	ds_read_b128 v[220:223], v155 offset:38912
	ds_read_b128 v[224:227], v155 offset:39936
	global_load_lds_dwordx4 v[234:235], off
	v_lshl_add_u64 v[234:235], s[26:27], 0, v[134:135]
	s_mov_b32 m0, s44
	s_nop 0
	global_load_lds_dwordx4 v[234:235], off
	s_waitcnt vmcnt(8)
	s_waitcnt lgkmcnt(0)
	s_barrier
	s_waitcnt lgkmcnt(0)
	v_mfma_f32_16x16x32_bf16 v[128:131], v[148:151], v[196:199], v[128:131]
	v_mfma_f32_16x16x32_bf16 v[124:127], v[160:163], v[196:199], v[124:127]
	v_mfma_f32_16x16x32_bf16 v[112:115], v[148:151], v[204:207], v[112:115]
	v_mfma_f32_16x16x32_bf16 v[108:111], v[160:163], v[204:207], v[108:111]
	v_mfma_f32_16x16x32_bf16 v[96:99], v[148:151], v[212:215], v[96:99]
	v_mfma_f32_16x16x32_bf16 v[92:95], v[160:163], v[212:215], v[92:95]
	v_mfma_f32_16x16x32_bf16 v[80:83], v[148:151], v[220:223], v[80:83]
	v_mfma_f32_16x16x32_bf16 v[76:79], v[160:163], v[220:223], v[76:79]
	v_mfma_f32_16x16x32_bf16 v[128:131], v[156:159], v[200:203], v[128:131]
	v_mfma_f32_16x16x32_bf16 v[124:127], v[164:167], v[200:203], v[124:127]
	v_mfma_f32_16x16x32_bf16 v[112:115], v[156:159], v[208:211], v[112:115]
	v_mfma_f32_16x16x32_bf16 v[108:111], v[164:167], v[208:211], v[108:111]
	v_mfma_f32_16x16x32_bf16 v[96:99], v[156:159], v[216:219], v[96:99]
	v_mfma_f32_16x16x32_bf16 v[92:95], v[164:167], v[216:219], v[92:95]
	v_mfma_f32_16x16x32_bf16 v[80:83], v[156:159], v[224:227], v[80:83]
	v_mfma_f32_16x16x32_bf16 v[76:79], v[164:167], v[224:227], v[76:79]
	v_mfma_f32_16x16x32_bf16 v[120:123], v[168:171], v[196:199], v[120:123]
	v_mfma_f32_16x16x32_bf16 v[116:119], v[188:191], v[196:199], v[116:119]
	v_mfma_f32_16x16x32_bf16 v[104:107], v[168:171], v[204:207], v[104:107]
	v_mfma_f32_16x16x32_bf16 v[100:103], v[188:191], v[204:207], v[100:103]
	v_mfma_f32_16x16x32_bf16 v[88:91], v[168:171], v[212:215], v[88:91]
	v_mfma_f32_16x16x32_bf16 v[84:87], v[188:191], v[212:215], v[84:87]
	v_mfma_f32_16x16x32_bf16 v[72:75], v[168:171], v[220:223], v[72:75]
	v_mfma_f32_16x16x32_bf16 v[68:71], v[188:191], v[220:223], v[68:71]
	v_mfma_f32_16x16x32_bf16 v[120:123], v[184:187], v[200:203], v[120:123]
	v_mfma_f32_16x16x32_bf16 v[116:119], v[192:195], v[200:203], v[116:119]
	v_mfma_f32_16x16x32_bf16 v[104:107], v[184:187], v[208:211], v[104:107]
	v_mfma_f32_16x16x32_bf16 v[100:103], v[192:195], v[208:211], v[100:103]
	v_mfma_f32_16x16x32_bf16 v[88:91], v[184:187], v[216:219], v[88:91]
	v_mfma_f32_16x16x32_bf16 v[84:87], v[192:195], v[216:219], v[84:87]
	v_mfma_f32_16x16x32_bf16 v[72:75], v[184:187], v[224:227], v[72:75]
	v_mfma_f32_16x16x32_bf16 v[68:71], v[192:195], v[224:227], v[68:71]
	s_barrier
; #define PG8_STAGE(bufoff, gbase, voff) do { _Pragma("unroll") for (int _i = 0; _i < 2; ++_i) \
;         __builtin_amdgcn_global_load_lds((const unsigned*)((const char*)(gbase) + (voff)[_i]), (PG8_LAS unsigned*)(lds + (bufoff) + ldsw + _i * 8192), 16, 0, 0); } while (0)
; #define PG8_LDA(dst, b, h) do { _Pragma("unroll") for (int m = 0; m < 4; ++m) _Pragma("unroll") for (int k = 0; k < 2; ++k) dst[m][k] = *(const PG8_LAS bf16x8*)(lds + PG8_SA(b, h) + aoff + m * 2048 + k * 1024); } while (0)
; #define PG8_MMA(ai, bj, At, Bt) do { __builtin_amdgcn_s_setprio(1); _Pragma("unroll") for (int m = 0; m < 4; ++m) _Pragma("unroll") for (int n = 0; n < 2; ++n) _Pragma("unroll") for (int k = 0; k < 2; ++k) \
;         acc[ai][bj][m][n] = __builtin_amdgcn_mfma_f32_16x16x32_bf16(Bt[n][k], At[m][k], acc[ai][bj][m][n], 0, 0, 0); __builtin_amdgcn_s_setprio(0); } while (0)
; #define PG8_WAIT_V(n) asm volatile("s_waitcnt vmcnt(" #n ")" ::: "memory")
; #define PG8_WAIT_L(n) asm volatile("s_waitcnt lgkmcnt(" #n ")" ::: "memory")
; #define PG8_BAR __builtin_amdgcn_s_barrier()
; #define PG8_SCHED __builtin_amdgcn_sched_barrier(0)
; template <class Epi, class Sched, bool ALIGN_EPI = false, bool SP2 = false>
; __device__ __forceinline__ void gemm_phase(PG8_LAS unsigned char* lds, const Gemm g, const Sched& S, const Epi& E) {
;     ...
;             PG8_LDA(At, 1, 1); PG8_STAGE(PG8_SB(1, 0), b3, voffB); PG8_STAGE(PG8_SB(1, 1), b3 + hstep, voffB); PG8_STAGE(PG8_SA(1, 0), a3, voffA);
;             PG8_WAIT_V(8); PG8_WAIT_L(0); PG8_BAR; PG8_MMA(1, 0, At, B0); PG8_MMA(1, 1, At, B1); PG8_BAR; PG8_SCHED;
;     ...
;         if constexpr (ALIGN_EPI) { if (wr == 0) PG8_BAR; }
	s_add_i32 s26, s55, s24
	v_lshl_add_u64 v[144:145], v[144:145], 0, s[10:11]
	s_mov_b32 m0, s26
	global_load_lds_dwordx4 v[144:145], off
	s_add_i32 m0, s26, 0x2000
	s_add_u32 s26, s40, 0x80080
	v_lshl_add_u64 v[144:145], v[228:229], 0, s[10:11]
	s_addc_u32 s27, s41, 0
	s_add_i32 s40, s56, s24
	global_load_lds_dwordx4 v[144:145], off
	v_lshl_add_u64 v[144:145], s[26:27], 0, v[174:175]
	s_mov_b32 m0, s40
	s_nop 0
	global_load_lds_dwordx4 v[144:145], off
	v_lshl_add_u64 v[144:145], s[26:27], 0, v[132:133]
	s_add_i32 m0, s40, 0x2000
	s_nop 0
	global_load_lds_dwordx4 v[144:145], off
	v_lshl_add_u64 v[144:145], v[230:231], 0, s[10:11]
	s_mov_b32 m0, s20
	s_nop 0
	global_load_lds_dwordx4 v[144:145], off
	v_lshl_add_u64 v[144:145], v[232:233], 0, s[10:11]
	s_mov_b32 m0, s45
	s_nop 0
	global_load_lds_dwordx4 v[144:145], off
	ds_read_b128 v[196:199], v155 offset:49152
	ds_read_b128 v[200:203], v155 offset:50176
	ds_read_b128 v[204:207], v155 offset:51200
	ds_read_b128 v[208:211], v155 offset:52224
	ds_read_b128 v[212:215], v155 offset:53248
	ds_read_b128 v[216:219], v155 offset:54272
	ds_read_b128 v[220:223], v155 offset:55296
	ds_read_b128 v[224:227], v155 offset:56320
	s_waitcnt vmcnt(8)
	s_waitcnt lgkmcnt(0)
	s_barrier
	s_waitcnt lgkmcnt(0)
	v_mfma_f32_16x16x32_bf16 v[64:67], v[148:151], v[196:199], v[64:67]
	v_mfma_f32_16x16x32_bf16 v[60:63], v[160:163], v[196:199], v[60:63]
	v_mfma_f32_16x16x32_bf16 v[52:55], v[148:151], v[204:207], v[52:55]
	v_mfma_f32_16x16x32_bf16 v[44:47], v[160:163], v[204:207], v[44:47]
	v_mfma_f32_16x16x32_bf16 v[36:39], v[148:151], v[212:215], v[36:39]
	v_mfma_f32_16x16x32_bf16 v[28:31], v[160:163], v[212:215], v[28:31]
	v_mfma_f32_16x16x32_bf16 v[20:23], v[148:151], v[220:223], v[20:23]
	v_mfma_f32_16x16x32_bf16 v[12:15], v[160:163], v[220:223], v[12:15]
	v_mfma_f32_16x16x32_bf16 v[64:67], v[156:159], v[200:203], v[64:67]
	v_mfma_f32_16x16x32_bf16 v[60:63], v[164:167], v[200:203], v[60:63]
	v_mfma_f32_16x16x32_bf16 v[52:55], v[156:159], v[208:211], v[52:55]
	v_mfma_f32_16x16x32_bf16 v[44:47], v[164:167], v[208:211], v[44:47]
	v_mfma_f32_16x16x32_bf16 v[36:39], v[156:159], v[216:219], v[36:39]
	v_mfma_f32_16x16x32_bf16 v[28:31], v[164:167], v[216:219], v[28:31]
	v_mfma_f32_16x16x32_bf16 v[20:23], v[156:159], v[224:227], v[20:23]
	v_mfma_f32_16x16x32_bf16 v[12:15], v[164:167], v[224:227], v[12:15]
	v_mfma_f32_16x16x32_bf16 v[56:59], v[168:171], v[196:199], v[56:59]
	v_mfma_f32_16x16x32_bf16 v[48:51], v[188:191], v[196:199], v[48:51]
	v_mfma_f32_16x16x32_bf16 v[40:43], v[168:171], v[204:207], v[40:43]
	v_mfma_f32_16x16x32_bf16 v[32:35], v[188:191], v[204:207], v[32:35]
	v_mfma_f32_16x16x32_bf16 v[24:27], v[168:171], v[212:215], v[24:27]
	v_mfma_f32_16x16x32_bf16 v[16:19], v[188:191], v[212:215], v[16:19]
	v_mfma_f32_16x16x32_bf16 v[8:11], v[168:171], v[220:223], v[8:11]
	v_mfma_f32_16x16x32_bf16 v[4:7], v[188:191], v[220:223], v[4:7]
	v_mfma_f32_16x16x32_bf16 v[56:59], v[184:187], v[200:203], v[56:59]
	v_mfma_f32_16x16x32_bf16 v[48:51], v[192:195], v[200:203], v[48:51]
	v_mfma_f32_16x16x32_bf16 v[40:43], v[184:187], v[208:211], v[40:43]
	v_mfma_f32_16x16x32_bf16 v[32:35], v[192:195], v[208:211], v[32:35]
	v_mfma_f32_16x16x32_bf16 v[24:27], v[184:187], v[216:219], v[24:27]
	v_mfma_f32_16x16x32_bf16 v[16:19], v[192:195], v[216:219], v[16:19]
	v_mfma_f32_16x16x32_bf16 v[8:11], v[184:187], v[224:227], v[8:11]
	v_mfma_f32_16x16x32_bf16 v[4:7], v[192:195], v[224:227], v[4:7]
	s_barrier
	s_add_i32 s54, s54, 2
	s_add_u32 s52, s52, 0x100
	s_addc_u32 s53, s53, 0
	s_add_u32 s38, s38, 0x100
	s_addc_u32 s39, s39, 0
	s_cmp_gt_u32 s54, 29
	s_cbranch_scc0 .LBB0_86
	s_and_b64 vcc, exec, s[16:17]
	s_cbranch_vccz .LBB0_89
	s_barrier

; #define PG8_STAGE(bufoff, gbase, voff) do { _Pragma("unroll") for (int _i = 0; _i < 2; ++_i) \
;         __builtin_amdgcn_global_load_lds((const unsigned*)((const char*)(gbase) + (voff)[_i]), (PG8_LAS unsigned*)(lds + (bufoff) + ldsw + _i * 8192), 16, 0, 0); } while (0)
; #define PG8_LDA(dst, b, h) do { _Pragma("unroll") for (int m = 0; m < 4; ++m) _Pragma("unroll") for (int k = 0; k < 2; ++k) dst[m][k] = *(const PG8_LAS bf16x8*)(lds + PG8_SA(b, h) + aoff + m * 2048 + k * 1024); } while (0)
; #define PG8_LDB(dst, b, h) do { _Pragma("unroll") for (int n = 0; n < 2; ++n) _Pragma("unroll") for (int k = 0; k < 2; ++k) dst[n][k] = *(const PG8_LAS bf16x8*)(lds + PG8_SB(b, h) + boff + n * 2048 + k * 1024); } while (0)
; #define PG8_MMA(ai, bj, At, Bt) do { __builtin_amdgcn_s_setprio(1); _Pragma("unroll") for (int m = 0; m < 4; ++m) _Pragma("unroll") for (int n = 0; n < 2; ++n) _Pragma("unroll") for (int k = 0; k < 2; ++k) \
;         acc[ai][bj][m][n] = __builtin_amdgcn_mfma_f32_16x16x32_bf16(Bt[n][k], At[m][k], acc[ai][bj][m][n], 0, 0, 0); __builtin_amdgcn_s_setprio(0); } while (0)
; #define PG8_WAIT_V(n) asm volatile("s_waitcnt vmcnt(" #n ")" ::: "memory")
; #define PG8_WAIT_L(n) asm volatile("s_waitcnt lgkmcnt(" #n ")" ::: "memory")
; #define PG8_BAR __builtin_amdgcn_s_barrier()
; template <class Epi, class Sched, bool ALIGN_EPI = false, bool SP2 = false>
; __device__ __forceinline__ void gemm_phase(PG8_LAS unsigned char* lds, const Gemm g, const Sched& S, const Epi& E) {
;     ...
;             const char* a1 = cA + (size_t)(t + 1) * kstep;
;             const char* a2 = last ? nA : cA + (size_t)(t + 2) * kstep; const char* b2 = last ? nB : cB + (size_t)(t + 2) * kstep;
;             const char* a3 = a2 + kstep; const char* b3 = b2 + kstep;
;             if (last && has_next) S.a_ready(nxt);
;             if constexpr (SP2) {
;             PG8_LDB(B0, 0, 0); PG8_LDB(B1, 0, 1); PG8_SCHED; PG8_LDA(At, 0, 0); PG8_STAGE(PG8_SA(1, 1), a1 + hstep, voffA);
;             PG8_WAIT_V(8); PG8_WAIT_L(0); PG8_BAR; PG8_MMA(0, 0, At, B0); PG8_MMA(0, 1, At, B1); PG8_BAR; PG8_SCHED;
;             PG8_LDA(At, 0, 1); PG8_STAGE(PG8_SB(0, 0), b2, voffB); PG8_STAGE(PG8_SB(0, 1), b2 + hstep, voffB); PG8_STAGE(PG8_SA(0, 0), a2, voffA);
;             PG8_WAIT_V(8); PG8_WAIT_L(0); PG8_BAR; PG8_MMA(1, 0, At, B0); PG8_MMA(1, 1, At, B1); PG8_BAR; PG8_SCHED;
.Lprio_done_407:
.LBB0_407:
	s_add_u32 s14, s0, 0xfff80080
	s_addc_u32 s15, s1, -1
	s_add_i32 s59, 0, 0x10000
	s_cmp_eq_u32 s58, 28
	s_cselect_b32 s17, s23, s15
	s_cselect_b32 s16, s24, s14
	s_cselect_b32 s15, s25, s57
	s_cselect_b32 s14, s49, s51
	s_add_i32 s62, 0, 0x14000
	v_add_u32_e32 v154, s59, v171
	v_add_u32_e32 v185, s62, v171
	ds_read_b128 v[100:103], v154
	ds_read_b128 v[104:107], v154 offset:1024
	ds_read_b128 v[140:143], v154 offset:2048
	ds_read_b128 v[154:157], v154 offset:3072
	ds_read_b128 v[158:161], v185
	ds_read_b128 v[162:165], v185 offset:1024
	ds_read_b128 v[166:169], v185 offset:2048
	ds_read_b128 v[186:189], v185 offset:3072
	v_lshl_add_u64 v[222:223], s[0:1], 0, v[152:153]
	s_add_i32 m0, s29, 0xc000
	ds_read_b128 v[190:193], v184
	ds_read_b128 v[194:197], v184 offset:1024
	ds_read_b128 v[198:201], v184 offset:2048
	ds_read_b128 v[202:205], v184 offset:3072
	ds_read_b128 v[206:209], v184 offset:4096
	ds_read_b128 v[210:213], v184 offset:5120
	ds_read_b128 v[214:217], v184 offset:6144
	ds_read_b128 v[218:221], v184 offset:7168
	global_load_lds_dwordx4 v[222:223], off
	v_lshl_add_u64 v[222:223], s[0:1], 0, v[150:151]
	s_add_i32 m0, s29, 0xe000
	s_nop 0
	global_load_lds_dwordx4 v[222:223], off
	s_waitcnt vmcnt(8)
	s_waitcnt lgkmcnt(0)
	s_barrier
	s_waitcnt lgkmcnt(0)
	v_mfma_f32_16x16x32_bf16 v[136:139], v[100:103], v[190:193], v[136:139]
	v_mfma_f32_16x16x32_bf16 v[132:135], v[140:143], v[190:193], v[132:135]
	v_mfma_f32_16x16x32_bf16 v[128:131], v[100:103], v[198:201], v[128:131]
	v_mfma_f32_16x16x32_bf16 v[124:127], v[140:143], v[198:201], v[124:127]
	v_mfma_f32_16x16x32_bf16 v[120:123], v[100:103], v[206:209], v[120:123]
	v_mfma_f32_16x16x32_bf16 v[116:119], v[140:143], v[206:209], v[116:119]
	v_mfma_f32_16x16x32_bf16 v[112:115], v[100:103], v[214:217], v[112:115]
	v_mfma_f32_16x16x32_bf16 v[108:111], v[140:143], v[214:217], v[108:111]
	v_mfma_f32_16x16x32_bf16 v[136:139], v[104:107], v[194:197], v[136:139]
	v_mfma_f32_16x16x32_bf16 v[132:135], v[154:157], v[194:197], v[132:135]
	v_mfma_f32_16x16x32_bf16 v[128:131], v[104:107], v[202:205], v[128:131]
	v_mfma_f32_16x16x32_bf16 v[124:127], v[154:157], v[202:205], v[124:127]
	v_mfma_f32_16x16x32_bf16 v[120:123], v[104:107], v[210:213], v[120:123]
	v_mfma_f32_16x16x32_bf16 v[116:119], v[154:157], v[210:213], v[116:119]
	v_mfma_f32_16x16x32_bf16 v[112:115], v[104:107], v[218:221], v[112:115]
	v_mfma_f32_16x16x32_bf16 v[108:111], v[154:157], v[218:221], v[108:111]
	v_mfma_f32_16x16x32_bf16 v[64:67], v[158:161], v[190:193], v[64:67]
	v_mfma_f32_16x16x32_bf16 v[60:63], v[166:169], v[190:193], v[60:63]
	v_mfma_f32_16x16x32_bf16 v[56:59], v[158:161], v[198:201], v[56:59]
	v_mfma_f32_16x16x32_bf16 v[52:55], v[166:169], v[198:201], v[52:55]
	v_mfma_f32_16x16x32_bf16 v[48:51], v[158:161], v[206:209], v[48:51]
	v_mfma_f32_16x16x32_bf16 v[44:47], v[166:169], v[206:209], v[44:47]
	v_mfma_f32_16x16x32_bf16 v[40:43], v[158:161], v[214:217], v[40:43]
	v_mfma_f32_16x16x32_bf16 v[36:39], v[166:169], v[214:217], v[36:39]
	v_mfma_f32_16x16x32_bf16 v[64:67], v[162:165], v[194:197], v[64:67]
	v_mfma_f32_16x16x32_bf16 v[60:63], v[186:189], v[194:197], v[60:63]
	v_mfma_f32_16x16x32_bf16 v[56:59], v[162:165], v[202:205], v[56:59]
	v_mfma_f32_16x16x32_bf16 v[52:55], v[186:189], v[202:205], v[52:55]
	v_mfma_f32_16x16x32_bf16 v[48:51], v[162:165], v[210:213], v[48:51]
	v_mfma_f32_16x16x32_bf16 v[44:47], v[186:189], v[210:213], v[44:47]
	v_mfma_f32_16x16x32_bf16 v[40:43], v[162:165], v[218:221], v[40:43]
	v_mfma_f32_16x16x32_bf16 v[36:39], v[186:189], v[218:221], v[36:39]
	s_barrier
	s_add_i32 s59, s59, s28
	v_lshl_add_u64 v[222:223], s[14:15], 0, v[174:175]
	s_mov_b32 m0, s59
	global_load_lds_dwordx4 v[222:223], off
	s_add_i32 m0, s59, 0x2000
	s_add_u32 s60, s14, 0x80000
	v_lshl_add_u64 v[224:225], s[14:15], 0, v[144:145]
	s_addc_u32 s61, s15, 0
	s_add_i32 s59, s62, s28
	global_load_lds_dwordx4 v[224:225], off
	v_lshl_add_u64 v[226:227], s[60:61], 0, v[174:175]
	s_mov_b32 m0, s59
	v_lshl_add_u64 v[228:229], s[16:17], 0, v[146:147]
	global_load_lds_dwordx4 v[226:227], off
	v_lshl_add_u64 v[226:227], s[60:61], 0, v[144:145]
	s_add_i32 m0, s59, 0x2000
	s_nop 0
	global_load_lds_dwordx4 v[226:227], off
	v_lshl_add_u64 v[226:227], s[16:17], 0, v[148:149]
	s_mov_b32 m0, s29
	s_nop 0
	global_load_lds_dwordx4 v[226:227], off
	s_mov_b32 m0, s30
	s_nop 0
	global_load_lds_dwordx4 v[228:229], off
	ds_read_b128 v[190:193], v184 offset:16384
	ds_read_b128 v[194:197], v184 offset:17408
	ds_read_b128 v[198:201], v184 offset:18432
	ds_read_b128 v[202:205], v184 offset:19456
	ds_read_b128 v[206:209], v184 offset:20480
	ds_read_b128 v[210:213], v184 offset:21504
	ds_read_b128 v[214:217], v184 offset:22528
	ds_read_b128 v[218:221], v184 offset:23552
	s_waitcnt vmcnt(8)
	s_waitcnt lgkmcnt(0)
	s_barrier
; #define PG8_STAGE(bufoff, gbase, voff) do { _Pragma("unroll") for (int _i = 0; _i < 2; ++_i) \
;         __builtin_amdgcn_global_load_lds((const unsigned*)((const char*)(gbase) + (voff)[_i]), (PG8_LAS unsigned*)(lds + (bufoff) + ldsw + _i * 8192), 16, 0, 0); } while (0)
; #define PG8_LDA(dst, b, h) do { _Pragma("unroll") for (int m = 0; m < 4; ++m) _Pragma("unroll") for (int k = 0; k < 2; ++k) dst[m][k] = *(const PG8_LAS bf16x8*)(lds + PG8_SA(b, h) + aoff + m * 2048 + k * 1024); } while (0)
; #define PG8_LDB(dst, b, h) do { _Pragma("unroll") for (int n = 0; n < 2; ++n) _Pragma("unroll") for (int k = 0; k < 2; ++k) dst[n][k] = *(const PG8_LAS bf16x8*)(lds + PG8_SB(b, h) + boff + n * 2048 + k * 1024); } while (0)
; #define PG8_MMA(ai, bj, At, Bt) do { __builtin_amdgcn_s_setprio(1); _Pragma("unroll") for (int m = 0; m < 4; ++m) _Pragma("unroll") for (int n = 0; n < 2; ++n) _Pragma("unroll") for (int k = 0; k < 2; ++k) \
;         acc[ai][bj][m][n] = __builtin_amdgcn_mfma_f32_16x16x32_bf16(Bt[n][k], At[m][k], acc[ai][bj][m][n], 0, 0, 0); __builtin_amdgcn_s_setprio(0); } while (0)
; #define PG8_WAIT_V(n) asm volatile("s_waitcnt vmcnt(" #n ")" ::: "memory")
; #define PG8_WAIT_L(n) asm volatile("s_waitcnt lgkmcnt(" #n ")" ::: "memory")
; #define PG8_BAR __builtin_amdgcn_s_barrier()
; #define PG8_SCHED __builtin_amdgcn_sched_barrier(0)
; template <class Epi, class Sched, bool ALIGN_EPI = false, bool SP2 = false>
; __device__ __forceinline__ void gemm_phase(PG8_LAS unsigned char* lds, const Gemm g, const Sched& S, const Epi& E) {
;     ...
;             PG8_LDA(At, 0, 1); PG8_STAGE(PG8_SB(0, 0), b2, voffB); PG8_STAGE(PG8_SB(0, 1), b2 + hstep, voffB); PG8_STAGE(PG8_SA(0, 0), a2, voffA);
;             PG8_WAIT_V(8); PG8_WAIT_L(0); PG8_BAR; PG8_MMA(1, 0, At, B0); PG8_MMA(1, 1, At, B1); PG8_BAR; PG8_SCHED;
;             PG8_LDB(B0, 1, 0); PG8_LDB(B1, 1, 1); PG8_SCHED; PG8_LDA(At, 1, 0); PG8_STAGE(PG8_SA(0, 1), a2 + hstep, voffA);
;             PG8_WAIT_V(8); PG8_WAIT_L(0); PG8_BAR; PG8_MMA(0, 0, At, B0); PG8_MMA(0, 1, At, B1); PG8_BAR; PG8_SCHED;
	s_waitcnt lgkmcnt(0)
	v_mfma_f32_16x16x32_bf16 v[96:99], v[100:103], v[190:193], v[96:99]
	v_mfma_f32_16x16x32_bf16 v[92:95], v[140:143], v[190:193], v[92:95]
	v_mfma_f32_16x16x32_bf16 v[88:91], v[100:103], v[198:201], v[88:91]
	v_mfma_f32_16x16x32_bf16 v[84:87], v[140:143], v[198:201], v[84:87]
	v_mfma_f32_16x16x32_bf16 v[80:83], v[100:103], v[206:209], v[80:83]
	v_mfma_f32_16x16x32_bf16 v[76:79], v[140:143], v[206:209], v[76:79]
	v_mfma_f32_16x16x32_bf16 v[72:75], v[100:103], v[214:217], v[72:75]
	v_mfma_f32_16x16x32_bf16 v[68:71], v[140:143], v[214:217], v[68:71]
	v_mfma_f32_16x16x32_bf16 v[96:99], v[104:107], v[194:197], v[96:99]
	v_mfma_f32_16x16x32_bf16 v[92:95], v[154:157], v[194:197], v[92:95]
	v_mfma_f32_16x16x32_bf16 v[88:91], v[104:107], v[202:205], v[88:91]
	v_mfma_f32_16x16x32_bf16 v[84:87], v[154:157], v[202:205], v[84:87]
	v_mfma_f32_16x16x32_bf16 v[80:83], v[104:107], v[210:213], v[80:83]
	v_mfma_f32_16x16x32_bf16 v[76:79], v[154:157], v[210:213], v[76:79]
	v_mfma_f32_16x16x32_bf16 v[72:75], v[104:107], v[218:221], v[72:75]
	v_mfma_f32_16x16x32_bf16 v[68:71], v[154:157], v[218:221], v[68:71]
	v_mfma_f32_16x16x32_bf16 v[32:35], v[158:161], v[190:193], v[32:35]
	v_mfma_f32_16x16x32_bf16 v[28:31], v[166:169], v[190:193], v[28:31]
	v_mfma_f32_16x16x32_bf16 v[24:27], v[158:161], v[198:201], v[24:27]
	v_mfma_f32_16x16x32_bf16 v[20:23], v[166:169], v[198:201], v[20:23]
	v_mfma_f32_16x16x32_bf16 v[16:19], v[158:161], v[206:209], v[16:19]
	v_mfma_f32_16x16x32_bf16 v[12:15], v[166:169], v[206:209], v[12:15]
	v_mfma_f32_16x16x32_bf16 v[8:11], v[158:161], v[214:217], v[8:11]
	v_mfma_f32_16x16x32_bf16 v[4:7], v[166:169], v[214:217], v[4:7]
	v_mfma_f32_16x16x32_bf16 v[32:35], v[162:165], v[194:197], v[32:35]
	v_mfma_f32_16x16x32_bf16 v[28:31], v[186:189], v[194:197], v[28:31]
	v_mfma_f32_16x16x32_bf16 v[24:27], v[162:165], v[202:205], v[24:27]
	v_mfma_f32_16x16x32_bf16 v[20:23], v[186:189], v[202:205], v[20:23]
	v_mfma_f32_16x16x32_bf16 v[16:19], v[162:165], v[210:213], v[16:19]
	v_mfma_f32_16x16x32_bf16 v[12:15], v[186:189], v[210:213], v[12:15]
	v_mfma_f32_16x16x32_bf16 v[8:11], v[162:165], v[218:221], v[8:11]
	v_mfma_f32_16x16x32_bf16 v[4:7], v[186:189], v[218:221], v[4:7]
	s_barrier
	s_add_i32 s59, 0, 0x18000
	s_add_i32 s60, 0, 0x1c000
	v_add_u32_e32 v154, s59, v171
	v_add_u32_e32 v185, s60, v171
	ds_read_b128 v[100:103], v154
	ds_read_b128 v[104:107], v154 offset:1024
	ds_read_b128 v[140:143], v154 offset:2048
	ds_read_b128 v[154:157], v154 offset:3072
	ds_read_b128 v[158:161], v185
	ds_read_b128 v[162:165], v185 offset:1024
	ds_read_b128 v[166:169], v185 offset:2048
	ds_read_b128 v[186:189], v185 offset:3072
	s_add_u32 s16, s16, 0x80000
	s_addc_u32 s17, s17, 0
	s_mov_b32 m0, s31
	v_lshl_add_u64 v[230:231], s[16:17], 0, v[148:149]
	ds_read_b128 v[190:193], v184 offset:32768
	ds_read_b128 v[194:197], v184 offset:33792
	ds_read_b128 v[198:201], v184 offset:34816
	ds_read_b128 v[202:205], v184 offset:35840
	ds_read_b128 v[206:209], v184 offset:36864
	ds_read_b128 v[210:213], v184 offset:37888
	ds_read_b128 v[214:217], v184 offset:38912
	ds_read_b128 v[218:221], v184 offset:39936
	global_load_lds_dwordx4 v[230:231], off
	v_lshl_add_u64 v[230:231], s[16:17], 0, v[146:147]
	s_mov_b32 m0, s34
	s_nop 0
	global_load_lds_dwordx4 v[230:231], off
	s_waitcnt vmcnt(8)
	s_waitcnt lgkmcnt(0)
	s_barrier
	s_waitcnt lgkmcnt(0)
	v_mfma_f32_16x16x32_bf16 v[136:139], v[100:103], v[190:193], v[136:139]
	v_mfma_f32_16x16x32_bf16 v[132:135], v[140:143], v[190:193], v[132:135]
	v_mfma_f32_16x16x32_bf16 v[128:131], v[100:103], v[198:201], v[128:131]
	v_mfma_f32_16x16x32_bf16 v[124:127], v[140:143], v[198:201], v[124:127]
	v_mfma_f32_16x16x32_bf16 v[120:123], v[100:103], v[206:209], v[120:123]
	v_mfma_f32_16x16x32_bf16 v[116:119], v[140:143], v[206:209], v[116:119]
	v_mfma_f32_16x16x32_bf16 v[112:115], v[100:103], v[214:217], v[112:115]
	v_mfma_f32_16x16x32_bf16 v[108:111], v[140:143], v[214:217], v[108:111]
	v_mfma_f32_16x16x32_bf16 v[136:139], v[104:107], v[194:197], v[136:139]
	v_mfma_f32_16x16x32_bf16 v[132:135], v[154:157], v[194:197], v[132:135]
	v_mfma_f32_16x16x32_bf16 v[128:131], v[104:107], v[202:205], v[128:131]
	v_mfma_f32_16x16x32_bf16 v[124:127], v[154:157], v[202:205], v[124:127]
	v_mfma_f32_16x16x32_bf16 v[120:123], v[104:107], v[210:213], v[120:123]
	v_mfma_f32_16x16x32_bf16 v[116:119], v[154:157], v[210:213], v[116:119]
	v_mfma_f32_16x16x32_bf16 v[112:115], v[104:107], v[218:221], v[112:115]
	v_mfma_f32_16x16x32_bf16 v[108:111], v[154:157], v[218:221], v[108:111]
	v_mfma_f32_16x16x32_bf16 v[64:67], v[158:161], v[190:193], v[64:67]
	v_mfma_f32_16x16x32_bf16 v[60:63], v[166:169], v[190:193], v[60:63]
	v_mfma_f32_16x16x32_bf16 v[56:59], v[158:161], v[198:201], v[56:59]
	v_mfma_f32_16x16x32_bf16 v[52:55], v[166:169], v[198:201], v[52:55]
	v_mfma_f32_16x16x32_bf16 v[48:51], v[158:161], v[206:209], v[48:51]
	v_mfma_f32_16x16x32_bf16 v[44:47], v[166:169], v[206:209], v[44:47]
	v_mfma_f32_16x16x32_bf16 v[40:43], v[158:161], v[214:217], v[40:43]
	v_mfma_f32_16x16x32_bf16 v[36:39], v[166:169], v[214:217], v[36:39]
	v_mfma_f32_16x16x32_bf16 v[64:67], v[162:165], v[194:197], v[64:67]
	v_mfma_f32_16x16x32_bf16 v[60:63], v[186:189], v[194:197], v[60:63]
	v_mfma_f32_16x16x32_bf16 v[56:59], v[162:165], v[202:205], v[56:59]
	v_mfma_f32_16x16x32_bf16 v[52:55], v[186:189], v[202:205], v[52:55]
	v_mfma_f32_16x16x32_bf16 v[48:51], v[162:165], v[210:213], v[48:51]
	v_mfma_f32_16x16x32_bf16 v[44:47], v[186:189], v[210:213], v[44:47]
	v_mfma_f32_16x16x32_bf16 v[40:43], v[162:165], v[218:221], v[40:43]
	v_mfma_f32_16x16x32_bf16 v[36:39], v[186:189], v[218:221], v[36:39]
	s_barrier
; #define PG8_STAGE(bufoff, gbase, voff) do { _Pragma("unroll") for (int _i = 0; _i < 2; ++_i) \
;         __builtin_amdgcn_global_load_lds((const unsigned*)((const char*)(gbase) + (voff)[_i]), (PG8_LAS unsigned*)(lds + (bufoff) + ldsw + _i * 8192), 16, 0, 0); } while (0)
; #define PG8_LDA(dst, b, h) do { _Pragma("unroll") for (int m = 0; m < 4; ++m) _Pragma("unroll") for (int k = 0; k < 2; ++k) dst[m][k] = *(const PG8_LAS bf16x8*)(lds + PG8_SA(b, h) + aoff + m * 2048 + k * 1024); } while (0)
; #define PG8_MMA(ai, bj, At, Bt) do { __builtin_amdgcn_s_setprio(1); _Pragma("unroll") for (int m = 0; m < 4; ++m) _Pragma("unroll") for (int n = 0; n < 2; ++n) _Pragma("unroll") for (int k = 0; k < 2; ++k) \
;         acc[ai][bj][m][n] = __builtin_amdgcn_mfma_f32_16x16x32_bf16(Bt[n][k], At[m][k], acc[ai][bj][m][n], 0, 0, 0); __builtin_amdgcn_s_setprio(0); } while (0)
; #define PG8_WAIT_V(n) asm volatile("s_waitcnt vmcnt(" #n ")" ::: "memory")
; #define PG8_WAIT_L(n) asm volatile("s_waitcnt lgkmcnt(" #n ")" ::: "memory")
; #define PG8_BAR __builtin_amdgcn_s_barrier()
; #define PG8_SCHED __builtin_amdgcn_sched_barrier(0)
; template <class Epi, class Sched, bool ALIGN_EPI = false, bool SP2 = false>
; __device__ __forceinline__ void gemm_phase(PG8_LAS unsigned char* lds, const Gemm g, const Sched& S, const Epi& E) {
;     ...
;             PG8_LDA(At, 1, 1); PG8_STAGE(PG8_SB(1, 0), b3, voffB); PG8_STAGE(PG8_SB(1, 1), b3 + hstep, voffB); PG8_STAGE(PG8_SA(1, 0), a3, voffA);
;             PG8_WAIT_V(8); PG8_WAIT_L(0); PG8_BAR; PG8_MMA(1, 0, At, B0); PG8_MMA(1, 1, At, B1); PG8_BAR; PG8_SCHED;
;     ...
;         if constexpr (ALIGN_EPI) { if (wr == 0) PG8_BAR; }
	s_add_i32 s16, s59, s28
	v_lshl_add_u64 v[222:223], v[222:223], 0, s[10:11]
	s_mov_b32 m0, s16
	global_load_lds_dwordx4 v[222:223], off
	s_add_i32 m0, s16, 0x2000
	s_add_u32 s14, s14, 0x80080
	v_lshl_add_u64 v[222:223], v[224:225], 0, s[10:11]
	s_addc_u32 s15, s15, 0
	s_add_i32 s16, s60, s28
	global_load_lds_dwordx4 v[222:223], off
	v_lshl_add_u64 v[222:223], s[14:15], 0, v[174:175]
	s_mov_b32 m0, s16
	s_nop 0
	global_load_lds_dwordx4 v[222:223], off
	v_lshl_add_u64 v[222:223], s[14:15], 0, v[144:145]
	s_add_i32 m0, s16, 0x2000
	s_nop 0
	global_load_lds_dwordx4 v[222:223], off
	v_lshl_add_u64 v[222:223], v[226:227], 0, s[10:11]
	s_mov_b32 m0, s35
	s_nop 0
	global_load_lds_dwordx4 v[222:223], off
	v_lshl_add_u64 v[222:223], v[228:229], 0, s[10:11]
	s_mov_b32 m0, s38
	s_nop 0
	global_load_lds_dwordx4 v[222:223], off
	ds_read_b128 v[190:193], v184 offset:49152
	ds_read_b128 v[194:197], v184 offset:50176
	ds_read_b128 v[198:201], v184 offset:51200
	ds_read_b128 v[202:205], v184 offset:52224
	ds_read_b128 v[206:209], v184 offset:53248
	ds_read_b128 v[210:213], v184 offset:54272
	ds_read_b128 v[214:217], v184 offset:55296
	ds_read_b128 v[218:221], v184 offset:56320
	s_waitcnt vmcnt(8)
	s_waitcnt lgkmcnt(0)
	s_barrier
	s_waitcnt lgkmcnt(0)
	v_mfma_f32_16x16x32_bf16 v[96:99], v[100:103], v[190:193], v[96:99]
	v_mfma_f32_16x16x32_bf16 v[92:95], v[140:143], v[190:193], v[92:95]
	v_mfma_f32_16x16x32_bf16 v[88:91], v[100:103], v[198:201], v[88:91]
	v_mfma_f32_16x16x32_bf16 v[84:87], v[140:143], v[198:201], v[84:87]
	v_mfma_f32_16x16x32_bf16 v[80:83], v[100:103], v[206:209], v[80:83]
	v_mfma_f32_16x16x32_bf16 v[76:79], v[140:143], v[206:209], v[76:79]
	v_mfma_f32_16x16x32_bf16 v[72:75], v[100:103], v[214:217], v[72:75]
	v_mfma_f32_16x16x32_bf16 v[68:71], v[140:143], v[214:217], v[68:71]
	v_mfma_f32_16x16x32_bf16 v[96:99], v[104:107], v[194:197], v[96:99]
	v_mfma_f32_16x16x32_bf16 v[92:95], v[154:157], v[194:197], v[92:95]
	v_mfma_f32_16x16x32_bf16 v[88:91], v[104:107], v[202:205], v[88:91]
	v_mfma_f32_16x16x32_bf16 v[84:87], v[154:157], v[202:205], v[84:87]
	v_mfma_f32_16x16x32_bf16 v[80:83], v[104:107], v[210:213], v[80:83]
	v_mfma_f32_16x16x32_bf16 v[76:79], v[154:157], v[210:213], v[76:79]
	v_mfma_f32_16x16x32_bf16 v[72:75], v[104:107], v[218:221], v[72:75]
	v_mfma_f32_16x16x32_bf16 v[68:71], v[154:157], v[218:221], v[68:71]
	v_mfma_f32_16x16x32_bf16 v[32:35], v[158:161], v[190:193], v[32:35]
	v_mfma_f32_16x16x32_bf16 v[28:31], v[166:169], v[190:193], v[28:31]
	v_mfma_f32_16x16x32_bf16 v[24:27], v[158:161], v[198:201], v[24:27]
	v_mfma_f32_16x16x32_bf16 v[20:23], v[166:169], v[198:201], v[20:23]
	v_mfma_f32_16x16x32_bf16 v[16:19], v[158:161], v[206:209], v[16:19]
	v_mfma_f32_16x16x32_bf16 v[12:15], v[166:169], v[206:209], v[12:15]
	v_mfma_f32_16x16x32_bf16 v[8:11], v[158:161], v[214:217], v[8:11]
	v_mfma_f32_16x16x32_bf16 v[4:7], v[166:169], v[214:217], v[4:7]
	v_mfma_f32_16x16x32_bf16 v[32:35], v[162:165], v[194:197], v[32:35]
	v_mfma_f32_16x16x32_bf16 v[28:31], v[186:189], v[194:197], v[28:31]
	v_mfma_f32_16x16x32_bf16 v[24:27], v[162:165], v[202:205], v[24:27]
	v_mfma_f32_16x16x32_bf16 v[20:23], v[186:189], v[202:205], v[20:23]
	v_mfma_f32_16x16x32_bf16 v[16:19], v[162:165], v[210:213], v[16:19]
	v_mfma_f32_16x16x32_bf16 v[12:15], v[186:189], v[210:213], v[12:15]
	v_mfma_f32_16x16x32_bf16 v[8:11], v[162:165], v[218:221], v[8:11]
	v_mfma_f32_16x16x32_bf16 v[4:7], v[186:189], v[218:221], v[4:7]
	s_barrier
	s_add_i32 s58, s58, 2
	s_add_u32 s51, s51, 0x100
	s_addc_u32 s57, s57, 0
	s_add_u32 s0, s0, 0x100
	s_addc_u32 s1, s1, 0
	s_cmp_gt_u32 s58, 29
	s_cbranch_scc0 .LBB0_407
	s_and_b64 vcc, exec, s[46:47]
	s_cbranch_vccz .LBB0_410
	s_barrier

; #define PG8_STAGE(bufoff, gbase, voff) do { _Pragma("unroll") for (int _i = 0; _i < 2; ++_i) \
;         __builtin_amdgcn_global_load_lds((const unsigned*)((const char*)(gbase) + (voff)[_i]), (PG8_LAS unsigned*)(lds + (bufoff) + ldsw + _i * 8192), 16, 0, 0); } while (0)
; #define PG8_LDA(dst, b, h) do { _Pragma("unroll") for (int m = 0; m < 4; ++m) _Pragma("unroll") for (int k = 0; k < 2; ++k) dst[m][k] = *(const PG8_LAS bf16x8*)(lds + PG8_SA(b, h) + aoff + m * 2048 + k * 1024); } while (0)
; #define PG8_LDB(dst, b, h) do { _Pragma("unroll") for (int n = 0; n < 2; ++n) _Pragma("unroll") for (int k = 0; k < 2; ++k) dst[n][k] = *(const PG8_LAS bf16x8*)(lds + PG8_SB(b, h) + boff + n * 2048 + k * 1024); } while (0)
; #define PG8_MMA(ai, bj, At, Bt) do { __builtin_amdgcn_s_setprio(1); _Pragma("unroll") for (int m = 0; m < 4; ++m) _Pragma("unroll") for (int n = 0; n < 2; ++n) _Pragma("unroll") for (int k = 0; k < 2; ++k) \
;         acc[ai][bj][m][n] = __builtin_amdgcn_mfma_f32_16x16x32_bf16(Bt[n][k], At[m][k], acc[ai][bj][m][n], 0, 0, 0); __builtin_amdgcn_s_setprio(0); } while (0)
; #define PG8_WAIT_V(n) asm volatile("s_waitcnt vmcnt(" #n ")" ::: "memory")
; #define PG8_WAIT_L(n) asm volatile("s_waitcnt lgkmcnt(" #n ")" ::: "memory")
; #define PG8_BAR __builtin_amdgcn_s_barrier()
; template <class Epi, class Sched, bool ALIGN_EPI = false, bool SP2 = false>
; __device__ __forceinline__ void gemm_phase(PG8_LAS unsigned char* lds, const Gemm g, const Sched& S, const Epi& E) {
;     ...
;             const char* a1 = cA + (size_t)(t + 1) * kstep;
;             const char* a2 = last ? nA : cA + (size_t)(t + 2) * kstep; const char* b2 = last ? nB : cB + (size_t)(t + 2) * kstep;
;             const char* a3 = a2 + kstep; const char* b3 = b2 + kstep;
;             if (last && has_next) S.a_ready(nxt);
;             if constexpr (SP2) {
;             PG8_LDB(B0, 0, 0); PG8_LDB(B1, 0, 1); PG8_SCHED; PG8_LDA(At, 0, 0); PG8_STAGE(PG8_SA(1, 1), a1 + hstep, voffA);
;             PG8_WAIT_V(8); PG8_WAIT_L(0); PG8_BAR; PG8_MMA(0, 0, At, B0); PG8_MMA(0, 1, At, B1); PG8_BAR; PG8_SCHED;
;             PG8_LDA(At, 0, 1); PG8_STAGE(PG8_SB(0, 0), b2, voffB); PG8_STAGE(PG8_SB(0, 1), b2 + hstep, voffB); PG8_STAGE(PG8_SA(0, 0), a2, voffA);
;             PG8_WAIT_V(8); PG8_WAIT_L(0); PG8_BAR; PG8_MMA(1, 0, At, B0); PG8_MMA(1, 1, At, B1); PG8_BAR; PG8_SCHED;
.Lprio_done_485:
.LBB0_485:
	s_add_u32 s14, s0, 0xfff00080
	s_addc_u32 s15, s1, -1
	s_add_i32 s61, 0, 0x10000
	s_cmp_eq_u32 s60, 60
	s_cselect_b32 s17, s23, s15
	s_cselect_b32 s16, s24, s14
	s_cselect_b32 s15, s25, s59
	s_cselect_b32 s14, s51, s53
	s_add_i32 s64, 0, 0x14000
	v_add_u32_e32 v144, s61, v188
	v_add_u32_e32 v170, s64, v188
	ds_read_b128 v[100:103], v144
	ds_read_b128 v[104:107], v144 offset:1024
	ds_read_b128 v[140:143], v144 offset:2048
	ds_read_b128 v[144:147], v144 offset:3072
	ds_read_b128 v[158:161], v170
	ds_read_b128 v[162:165], v170 offset:1024
	ds_read_b128 v[166:169], v170 offset:2048
	ds_read_b128 v[184:187], v170 offset:3072
	v_lshl_add_u64 v[170:171], s[0:1], 0, v[156:157]
	s_add_i32 m0, s29, 0xc000
	ds_read_b128 v[192:195], v190
	ds_read_b128 v[196:199], v190 offset:1024
	ds_read_b128 v[200:203], v190 offset:2048
	ds_read_b128 v[204:207], v190 offset:3072
	ds_read_b128 v[208:211], v190 offset:4096
	ds_read_b128 v[212:215], v190 offset:5120
	ds_read_b128 v[216:219], v190 offset:6144
	ds_read_b128 v[220:223], v190 offset:7168
	global_load_lds_dwordx4 v[170:171], off
	v_lshl_add_u64 v[170:171], s[0:1], 0, v[154:155]
	s_add_i32 m0, s29, 0xe000
	s_nop 0
	global_load_lds_dwordx4 v[170:171], off
	s_waitcnt vmcnt(8)
	s_waitcnt lgkmcnt(0)
	s_barrier
	s_waitcnt lgkmcnt(0)
	v_mfma_f32_16x16x32_bf16 v[136:139], v[100:103], v[192:195], v[136:139]
	v_mfma_f32_16x16x32_bf16 v[132:135], v[140:143], v[192:195], v[132:135]
	v_mfma_f32_16x16x32_bf16 v[128:131], v[100:103], v[200:203], v[128:131]
	v_mfma_f32_16x16x32_bf16 v[124:127], v[140:143], v[200:203], v[124:127]
	v_mfma_f32_16x16x32_bf16 v[120:123], v[100:103], v[208:211], v[120:123]
	v_mfma_f32_16x16x32_bf16 v[116:119], v[140:143], v[208:211], v[116:119]
	v_mfma_f32_16x16x32_bf16 v[112:115], v[100:103], v[216:219], v[112:115]
	v_mfma_f32_16x16x32_bf16 v[108:111], v[140:143], v[216:219], v[108:111]
	v_mfma_f32_16x16x32_bf16 v[136:139], v[104:107], v[196:199], v[136:139]
	v_mfma_f32_16x16x32_bf16 v[132:135], v[144:147], v[196:199], v[132:135]
	v_mfma_f32_16x16x32_bf16 v[128:131], v[104:107], v[204:207], v[128:131]
	v_mfma_f32_16x16x32_bf16 v[124:127], v[144:147], v[204:207], v[124:127]
	v_mfma_f32_16x16x32_bf16 v[120:123], v[104:107], v[212:215], v[120:123]
	v_mfma_f32_16x16x32_bf16 v[116:119], v[144:147], v[212:215], v[116:119]
	v_mfma_f32_16x16x32_bf16 v[112:115], v[104:107], v[220:223], v[112:115]
	v_mfma_f32_16x16x32_bf16 v[108:111], v[144:147], v[220:223], v[108:111]
	v_mfma_f32_16x16x32_bf16 v[64:67], v[158:161], v[192:195], v[64:67]
	v_mfma_f32_16x16x32_bf16 v[60:63], v[166:169], v[192:195], v[60:63]
	v_mfma_f32_16x16x32_bf16 v[56:59], v[158:161], v[200:203], v[56:59]
	v_mfma_f32_16x16x32_bf16 v[52:55], v[166:169], v[200:203], v[52:55]
	v_mfma_f32_16x16x32_bf16 v[48:51], v[158:161], v[208:211], v[48:51]
	v_mfma_f32_16x16x32_bf16 v[44:47], v[166:169], v[208:211], v[44:47]
	v_mfma_f32_16x16x32_bf16 v[40:43], v[158:161], v[216:219], v[40:43]
	v_mfma_f32_16x16x32_bf16 v[36:39], v[166:169], v[216:219], v[36:39]
	v_mfma_f32_16x16x32_bf16 v[64:67], v[162:165], v[196:199], v[64:67]
	v_mfma_f32_16x16x32_bf16 v[60:63], v[184:187], v[196:199], v[60:63]
	v_mfma_f32_16x16x32_bf16 v[56:59], v[162:165], v[204:207], v[56:59]
	v_mfma_f32_16x16x32_bf16 v[52:55], v[184:187], v[204:207], v[52:55]
	v_mfma_f32_16x16x32_bf16 v[48:51], v[162:165], v[212:215], v[48:51]
	v_mfma_f32_16x16x32_bf16 v[44:47], v[184:187], v[212:215], v[44:47]
	v_mfma_f32_16x16x32_bf16 v[40:43], v[162:165], v[220:223], v[40:43]
	v_mfma_f32_16x16x32_bf16 v[36:39], v[184:187], v[220:223], v[36:39]
	s_barrier
	s_add_i32 s61, s61, s28
	v_lshl_add_u64 v[170:171], s[14:15], 0, v[174:175]
	s_mov_b32 m0, s61
	global_load_lds_dwordx4 v[170:171], off
	s_add_i32 m0, s61, 0x2000
	s_add_u32 s62, s14, 0x100000
	v_lshl_add_u64 v[224:225], s[14:15], 0, v[148:149]
	s_addc_u32 s63, s15, 0
	s_add_i32 s61, s64, s28
	global_load_lds_dwordx4 v[224:225], off
	v_lshl_add_u64 v[226:227], s[62:63], 0, v[174:175]
	s_mov_b32 m0, s61
	v_lshl_add_u64 v[228:229], s[16:17], 0, v[150:151]
	global_load_lds_dwordx4 v[226:227], off
	v_lshl_add_u64 v[226:227], s[62:63], 0, v[148:149]
	s_add_i32 m0, s61, 0x2000
	s_nop 0
	global_load_lds_dwordx4 v[226:227], off
	v_lshl_add_u64 v[226:227], s[16:17], 0, v[152:153]
	s_mov_b32 m0, s29
	s_nop 0
	global_load_lds_dwordx4 v[226:227], off
	s_mov_b32 m0, s30
	s_nop 0
	global_load_lds_dwordx4 v[228:229], off
	ds_read_b128 v[192:195], v190 offset:16384
	ds_read_b128 v[196:199], v190 offset:17408
	ds_read_b128 v[200:203], v190 offset:18432
	ds_read_b128 v[204:207], v190 offset:19456
	ds_read_b128 v[208:211], v190 offset:20480
	ds_read_b128 v[212:215], v190 offset:21504
	ds_read_b128 v[216:219], v190 offset:22528
	ds_read_b128 v[220:223], v190 offset:23552
	s_waitcnt vmcnt(8)
	s_waitcnt lgkmcnt(0)
	s_barrier
; #define PG8_STAGE(bufoff, gbase, voff) do { _Pragma("unroll") for (int _i = 0; _i < 2; ++_i) \
;         __builtin_amdgcn_global_load_lds((const unsigned*)((const char*)(gbase) + (voff)[_i]), (PG8_LAS unsigned*)(lds + (bufoff) + ldsw + _i * 8192), 16, 0, 0); } while (0)
; #define PG8_LDA(dst, b, h) do { _Pragma("unroll") for (int m = 0; m < 4; ++m) _Pragma("unroll") for (int k = 0; k < 2; ++k) dst[m][k] = *(const PG8_LAS bf16x8*)(lds + PG8_SA(b, h) + aoff + m * 2048 + k * 1024); } while (0)
; #define PG8_LDB(dst, b, h) do { _Pragma("unroll") for (int n = 0; n < 2; ++n) _Pragma("unroll") for (int k = 0; k < 2; ++k) dst[n][k] = *(const PG8_LAS bf16x8*)(lds + PG8_SB(b, h) + boff + n * 2048 + k * 1024); } while (0)
; #define PG8_MMA(ai, bj, At, Bt) do { __builtin_amdgcn_s_setprio(1); _Pragma("unroll") for (int m = 0; m < 4; ++m) _Pragma("unroll") for (int n = 0; n < 2; ++n) _Pragma("unroll") for (int k = 0; k < 2; ++k) \
;         acc[ai][bj][m][n] = __builtin_amdgcn_mfma_f32_16x16x32_bf16(Bt[n][k], At[m][k], acc[ai][bj][m][n], 0, 0, 0); __builtin_amdgcn_s_setprio(0); } while (0)
; #define PG8_WAIT_V(n) asm volatile("s_waitcnt vmcnt(" #n ")" ::: "memory")
; #define PG8_WAIT_L(n) asm volatile("s_waitcnt lgkmcnt(" #n ")" ::: "memory")
; #define PG8_BAR __builtin_amdgcn_s_barrier()
; #define PG8_SCHED __builtin_amdgcn_sched_barrier(0)
; template <class Epi, class Sched, bool ALIGN_EPI = false, bool SP2 = false>
; __device__ __forceinline__ void gemm_phase(PG8_LAS unsigned char* lds, const Gemm g, const Sched& S, const Epi& E) {
;     ...
;             PG8_LDA(At, 0, 1); PG8_STAGE(PG8_SB(0, 0), b2, voffB); PG8_STAGE(PG8_SB(0, 1), b2 + hstep, voffB); PG8_STAGE(PG8_SA(0, 0), a2, voffA);
;             PG8_WAIT_V(8); PG8_WAIT_L(0); PG8_BAR; PG8_MMA(1, 0, At, B0); PG8_MMA(1, 1, At, B1); PG8_BAR; PG8_SCHED;
;             PG8_LDB(B0, 1, 0); PG8_LDB(B1, 1, 1); PG8_SCHED; PG8_LDA(At, 1, 0); PG8_STAGE(PG8_SA(0, 1), a2 + hstep, voffA);
;             PG8_WAIT_V(8); PG8_WAIT_L(0); PG8_BAR; PG8_MMA(0, 0, At, B0); PG8_MMA(0, 1, At, B1); PG8_BAR; PG8_SCHED;
	s_waitcnt lgkmcnt(0)
	v_mfma_f32_16x16x32_bf16 v[96:99], v[100:103], v[192:195], v[96:99]
	v_mfma_f32_16x16x32_bf16 v[92:95], v[140:143], v[192:195], v[92:95]
	v_mfma_f32_16x16x32_bf16 v[88:91], v[100:103], v[200:203], v[88:91]
	v_mfma_f32_16x16x32_bf16 v[84:87], v[140:143], v[200:203], v[84:87]
	v_mfma_f32_16x16x32_bf16 v[80:83], v[100:103], v[208:211], v[80:83]
	v_mfma_f32_16x16x32_bf16 v[76:79], v[140:143], v[208:211], v[76:79]
	v_mfma_f32_16x16x32_bf16 v[72:75], v[100:103], v[216:219], v[72:75]
	v_mfma_f32_16x16x32_bf16 v[68:71], v[140:143], v[216:219], v[68:71]
	v_mfma_f32_16x16x32_bf16 v[96:99], v[104:107], v[196:199], v[96:99]
	v_mfma_f32_16x16x32_bf16 v[92:95], v[144:147], v[196:199], v[92:95]
	v_mfma_f32_16x16x32_bf16 v[88:91], v[104:107], v[204:207], v[88:91]
	v_mfma_f32_16x16x32_bf16 v[84:87], v[144:147], v[204:207], v[84:87]
	v_mfma_f32_16x16x32_bf16 v[80:83], v[104:107], v[212:215], v[80:83]
	v_mfma_f32_16x16x32_bf16 v[76:79], v[144:147], v[212:215], v[76:79]
	v_mfma_f32_16x16x32_bf16 v[72:75], v[104:107], v[220:223], v[72:75]
	v_mfma_f32_16x16x32_bf16 v[68:71], v[144:147], v[220:223], v[68:71]
	v_mfma_f32_16x16x32_bf16 v[32:35], v[158:161], v[192:195], v[32:35]
	v_mfma_f32_16x16x32_bf16 v[28:31], v[166:169], v[192:195], v[28:31]
	v_mfma_f32_16x16x32_bf16 v[24:27], v[158:161], v[200:203], v[24:27]
	v_mfma_f32_16x16x32_bf16 v[20:23], v[166:169], v[200:203], v[20:23]
	v_mfma_f32_16x16x32_bf16 v[16:19], v[158:161], v[208:211], v[16:19]
	v_mfma_f32_16x16x32_bf16 v[12:15], v[166:169], v[208:211], v[12:15]
	v_mfma_f32_16x16x32_bf16 v[8:11], v[158:161], v[216:219], v[8:11]
	v_mfma_f32_16x16x32_bf16 v[4:7], v[166:169], v[216:219], v[4:7]
	v_mfma_f32_16x16x32_bf16 v[32:35], v[162:165], v[196:199], v[32:35]
	v_mfma_f32_16x16x32_bf16 v[28:31], v[184:187], v[196:199], v[28:31]
	v_mfma_f32_16x16x32_bf16 v[24:27], v[162:165], v[204:207], v[24:27]
	v_mfma_f32_16x16x32_bf16 v[20:23], v[184:187], v[204:207], v[20:23]
	v_mfma_f32_16x16x32_bf16 v[16:19], v[162:165], v[212:215], v[16:19]
	v_mfma_f32_16x16x32_bf16 v[12:15], v[184:187], v[212:215], v[12:15]
	v_mfma_f32_16x16x32_bf16 v[8:11], v[162:165], v[220:223], v[8:11]
	v_mfma_f32_16x16x32_bf16 v[4:7], v[184:187], v[220:223], v[4:7]
	s_barrier
	s_add_i32 s61, 0, 0x18000
	s_add_i32 s62, 0, 0x1c000
	v_add_u32_e32 v144, s61, v188
	v_add_u32_e32 v184, s62, v188
	ds_read_b128 v[100:103], v144
	ds_read_b128 v[104:107], v144 offset:1024
	ds_read_b128 v[140:143], v144 offset:2048
	ds_read_b128 v[144:147], v144 offset:3072
	ds_read_b128 v[158:161], v184
	ds_read_b128 v[162:165], v184 offset:1024
	ds_read_b128 v[166:169], v184 offset:2048
	ds_read_b128 v[184:187], v184 offset:3072
	s_add_u32 s16, s16, 0x100000
	s_addc_u32 s17, s17, 0
	s_mov_b32 m0, s31
	v_lshl_add_u64 v[230:231], s[16:17], 0, v[152:153]
	ds_read_b128 v[192:195], v190 offset:32768
	ds_read_b128 v[196:199], v190 offset:33792
	ds_read_b128 v[200:203], v190 offset:34816
	ds_read_b128 v[204:207], v190 offset:35840
	ds_read_b128 v[208:211], v190 offset:36864
	ds_read_b128 v[212:215], v190 offset:37888
	ds_read_b128 v[216:219], v190 offset:38912
	ds_read_b128 v[220:223], v190 offset:39936
	global_load_lds_dwordx4 v[230:231], off
	v_lshl_add_u64 v[230:231], s[16:17], 0, v[150:151]
	s_mov_b32 m0, s34
	s_nop 0
	global_load_lds_dwordx4 v[230:231], off
	s_waitcnt vmcnt(8)
	s_waitcnt lgkmcnt(0)
	s_barrier
	s_waitcnt lgkmcnt(0)
	v_mfma_f32_16x16x32_bf16 v[136:139], v[100:103], v[192:195], v[136:139]
	v_mfma_f32_16x16x32_bf16 v[132:135], v[140:143], v[192:195], v[132:135]
	v_mfma_f32_16x16x32_bf16 v[128:131], v[100:103], v[200:203], v[128:131]
	v_mfma_f32_16x16x32_bf16 v[124:127], v[140:143], v[200:203], v[124:127]
	v_mfma_f32_16x16x32_bf16 v[120:123], v[100:103], v[208:211], v[120:123]
	v_mfma_f32_16x16x32_bf16 v[116:119], v[140:143], v[208:211], v[116:119]
	v_mfma_f32_16x16x32_bf16 v[112:115], v[100:103], v[216:219], v[112:115]
	v_mfma_f32_16x16x32_bf16 v[108:111], v[140:143], v[216:219], v[108:111]
	v_mfma_f32_16x16x32_bf16 v[136:139], v[104:107], v[196:199], v[136:139]
	v_mfma_f32_16x16x32_bf16 v[132:135], v[144:147], v[196:199], v[132:135]
	v_mfma_f32_16x16x32_bf16 v[128:131], v[104:107], v[204:207], v[128:131]
	v_mfma_f32_16x16x32_bf16 v[124:127], v[144:147], v[204:207], v[124:127]
	v_mfma_f32_16x16x32_bf16 v[120:123], v[104:107], v[212:215], v[120:123]
	v_mfma_f32_16x16x32_bf16 v[116:119], v[144:147], v[212:215], v[116:119]
	v_mfma_f32_16x16x32_bf16 v[112:115], v[104:107], v[220:223], v[112:115]
	v_mfma_f32_16x16x32_bf16 v[108:111], v[144:147], v[220:223], v[108:111]
	v_mfma_f32_16x16x32_bf16 v[64:67], v[158:161], v[192:195], v[64:67]
	v_mfma_f32_16x16x32_bf16 v[60:63], v[166:169], v[192:195], v[60:63]
	v_mfma_f32_16x16x32_bf16 v[56:59], v[158:161], v[200:203], v[56:59]
	v_mfma_f32_16x16x32_bf16 v[52:55], v[166:169], v[200:203], v[52:55]
	v_mfma_f32_16x16x32_bf16 v[48:51], v[158:161], v[208:211], v[48:51]
	v_mfma_f32_16x16x32_bf16 v[44:47], v[166:169], v[208:211], v[44:47]
	v_mfma_f32_16x16x32_bf16 v[40:43], v[158:161], v[216:219], v[40:43]
	v_mfma_f32_16x16x32_bf16 v[36:39], v[166:169], v[216:219], v[36:39]
	v_mfma_f32_16x16x32_bf16 v[64:67], v[162:165], v[196:199], v[64:67]
	v_mfma_f32_16x16x32_bf16 v[60:63], v[184:187], v[196:199], v[60:63]
	v_mfma_f32_16x16x32_bf16 v[56:59], v[162:165], v[204:207], v[56:59]
	v_mfma_f32_16x16x32_bf16 v[52:55], v[184:187], v[204:207], v[52:55]
	v_mfma_f32_16x16x32_bf16 v[48:51], v[162:165], v[212:215], v[48:51]
	v_mfma_f32_16x16x32_bf16 v[44:47], v[184:187], v[212:215], v[44:47]
	v_mfma_f32_16x16x32_bf16 v[40:43], v[162:165], v[220:223], v[40:43]
	v_mfma_f32_16x16x32_bf16 v[36:39], v[184:187], v[220:223], v[36:39]
	s_barrier
; #define PG8_STAGE(bufoff, gbase, voff) do { _Pragma("unroll") for (int _i = 0; _i < 2; ++_i) \
;         __builtin_amdgcn_global_load_lds((const unsigned*)((const char*)(gbase) + (voff)[_i]), (PG8_LAS unsigned*)(lds + (bufoff) + ldsw + _i * 8192), 16, 0, 0); } while (0)
; #define PG8_LDA(dst, b, h) do { _Pragma("unroll") for (int m = 0; m < 4; ++m) _Pragma("unroll") for (int k = 0; k < 2; ++k) dst[m][k] = *(const PG8_LAS bf16x8*)(lds + PG8_SA(b, h) + aoff + m * 2048 + k * 1024); } while (0)
; #define PG8_MMA(ai, bj, At, Bt) do { __builtin_amdgcn_s_setprio(1); _Pragma("unroll") for (int m = 0; m < 4; ++m) _Pragma("unroll") for (int n = 0; n < 2; ++n) _Pragma("unroll") for (int k = 0; k < 2; ++k) \
;         acc[ai][bj][m][n] = __builtin_amdgcn_mfma_f32_16x16x32_bf16(Bt[n][k], At[m][k], acc[ai][bj][m][n], 0, 0, 0); __builtin_amdgcn_s_setprio(0); } while (0)
; #define PG8_WAIT_V(n) asm volatile("s_waitcnt vmcnt(" #n ")" ::: "memory")
; #define PG8_WAIT_L(n) asm volatile("s_waitcnt lgkmcnt(" #n ")" ::: "memory")
; #define PG8_BAR __builtin_amdgcn_s_barrier()
; #define PG8_SCHED __builtin_amdgcn_sched_barrier(0)
; template <class Epi, class Sched, bool ALIGN_EPI = false, bool SP2 = false>
; __device__ __forceinline__ void gemm_phase(PG8_LAS unsigned char* lds, const Gemm g, const Sched& S, const Epi& E) {
;     ...
;             PG8_LDA(At, 1, 1); PG8_STAGE(PG8_SB(1, 0), b3, voffB); PG8_STAGE(PG8_SB(1, 1), b3 + hstep, voffB); PG8_STAGE(PG8_SA(1, 0), a3, voffA);
;             PG8_WAIT_V(8); PG8_WAIT_L(0); PG8_BAR; PG8_MMA(1, 0, At, B0); PG8_MMA(1, 1, At, B1); PG8_BAR; PG8_SCHED;
;     ...
;         if constexpr (ALIGN_EPI) { if (wr == 0) PG8_BAR; }
	s_add_i32 s16, s61, s28
	v_lshl_add_u64 v[170:171], v[170:171], 0, s[10:11]
	s_mov_b32 m0, s16
	global_load_lds_dwordx4 v[170:171], off
	s_add_i32 m0, s16, 0x2000
	s_add_u32 s14, s14, 0x100080
	v_lshl_add_u64 v[170:171], v[224:225], 0, s[10:11]
	s_addc_u32 s15, s15, 0
	s_add_i32 s16, s62, s28
	global_load_lds_dwordx4 v[170:171], off
	v_lshl_add_u64 v[170:171], s[14:15], 0, v[174:175]
	s_mov_b32 m0, s16
	s_nop 0
	global_load_lds_dwordx4 v[170:171], off
	v_lshl_add_u64 v[170:171], s[14:15], 0, v[148:149]
	s_add_i32 m0, s16, 0x2000
	s_nop 0
	global_load_lds_dwordx4 v[170:171], off
	v_lshl_add_u64 v[170:171], v[226:227], 0, s[10:11]
	s_mov_b32 m0, s35
	s_nop 0
	global_load_lds_dwordx4 v[170:171], off
	v_lshl_add_u64 v[170:171], v[228:229], 0, s[10:11]
	s_mov_b32 m0, s38
	s_nop 0
	global_load_lds_dwordx4 v[170:171], off
	ds_read_b128 v[192:195], v190 offset:49152
	ds_read_b128 v[196:199], v190 offset:50176
	ds_read_b128 v[200:203], v190 offset:51200
	ds_read_b128 v[204:207], v190 offset:52224
	ds_read_b128 v[208:211], v190 offset:53248
	ds_read_b128 v[212:215], v190 offset:54272
	ds_read_b128 v[216:219], v190 offset:55296
	ds_read_b128 v[220:223], v190 offset:56320
	s_waitcnt vmcnt(8)
	s_waitcnt lgkmcnt(0)
	s_barrier
	s_waitcnt lgkmcnt(0)
	v_mfma_f32_16x16x32_bf16 v[96:99], v[100:103], v[192:195], v[96:99]
	v_mfma_f32_16x16x32_bf16 v[92:95], v[140:143], v[192:195], v[92:95]
	v_mfma_f32_16x16x32_bf16 v[88:91], v[100:103], v[200:203], v[88:91]
	v_mfma_f32_16x16x32_bf16 v[84:87], v[140:143], v[200:203], v[84:87]
	v_mfma_f32_16x16x32_bf16 v[80:83], v[100:103], v[208:211], v[80:83]
	v_mfma_f32_16x16x32_bf16 v[76:79], v[140:143], v[208:211], v[76:79]
	v_mfma_f32_16x16x32_bf16 v[72:75], v[100:103], v[216:219], v[72:75]
	v_mfma_f32_16x16x32_bf16 v[68:71], v[140:143], v[216:219], v[68:71]
	v_mfma_f32_16x16x32_bf16 v[96:99], v[104:107], v[196:199], v[96:99]
	v_mfma_f32_16x16x32_bf16 v[92:95], v[144:147], v[196:199], v[92:95]
	v_mfma_f32_16x16x32_bf16 v[88:91], v[104:107], v[204:207], v[88:91]
	v_mfma_f32_16x16x32_bf16 v[84:87], v[144:147], v[204:207], v[84:87]
	v_mfma_f32_16x16x32_bf16 v[80:83], v[104:107], v[212:215], v[80:83]
	v_mfma_f32_16x16x32_bf16 v[76:79], v[144:147], v[212:215], v[76:79]
	v_mfma_f32_16x16x32_bf16 v[72:75], v[104:107], v[220:223], v[72:75]
	v_mfma_f32_16x16x32_bf16 v[68:71], v[144:147], v[220:223], v[68:71]
	v_mfma_f32_16x16x32_bf16 v[32:35], v[158:161], v[192:195], v[32:35]
	v_mfma_f32_16x16x32_bf16 v[28:31], v[166:169], v[192:195], v[28:31]
	v_mfma_f32_16x16x32_bf16 v[24:27], v[158:161], v[200:203], v[24:27]
	v_mfma_f32_16x16x32_bf16 v[20:23], v[166:169], v[200:203], v[20:23]
	v_mfma_f32_16x16x32_bf16 v[16:19], v[158:161], v[208:211], v[16:19]
	v_mfma_f32_16x16x32_bf16 v[12:15], v[166:169], v[208:211], v[12:15]
	v_mfma_f32_16x16x32_bf16 v[8:11], v[158:161], v[216:219], v[8:11]
	v_mfma_f32_16x16x32_bf16 v[4:7], v[166:169], v[216:219], v[4:7]
	v_mfma_f32_16x16x32_bf16 v[32:35], v[162:165], v[196:199], v[32:35]
	v_mfma_f32_16x16x32_bf16 v[28:31], v[184:187], v[196:199], v[28:31]
	v_mfma_f32_16x16x32_bf16 v[24:27], v[162:165], v[204:207], v[24:27]
	v_mfma_f32_16x16x32_bf16 v[20:23], v[184:187], v[204:207], v[20:23]
	v_mfma_f32_16x16x32_bf16 v[16:19], v[162:165], v[212:215], v[16:19]
	v_mfma_f32_16x16x32_bf16 v[12:15], v[184:187], v[212:215], v[12:15]
	v_mfma_f32_16x16x32_bf16 v[8:11], v[162:165], v[220:223], v[8:11]
	v_mfma_f32_16x16x32_bf16 v[4:7], v[184:187], v[220:223], v[4:7]
	s_barrier
	s_add_i32 s60, s60, 2
	s_add_u32 s53, s53, 0x100
	s_addc_u32 s59, s59, 0
	s_add_u32 s0, s0, 0x100
	s_addc_u32 s1, s1, 0
	s_cmp_gt_u32 s60, 61
	s_cbranch_scc0 .LBB0_485
	s_and_b64 vcc, exec, s[48:49]
	s_cbranch_vccz .LBB0_488
	s_barrier

; #define PG8_STAGE(bufoff, gbase, voff) do { _Pragma("unroll") for (int _i = 0; _i < 2; ++_i) \
;         __builtin_amdgcn_global_load_lds((const unsigned*)((const char*)(gbase) + (voff)[_i]), (PG8_LAS unsigned*)(lds + (bufoff) + ldsw + _i * 8192), 16, 0, 0); } while (0)
; #define PG8_LDA(dst, b, h) do { _Pragma("unroll") for (int m = 0; m < 4; ++m) _Pragma("unroll") for (int k = 0; k < 2; ++k) dst[m][k] = *(const PG8_LAS bf16x8*)(lds + PG8_SA(b, h) + aoff + m * 2048 + k * 1024); } while (0)
; #define PG8_LDB(dst, b, h) do { _Pragma("unroll") for (int n = 0; n < 2; ++n) _Pragma("unroll") for (int k = 0; k < 2; ++k) dst[n][k] = *(const PG8_LAS bf16x8*)(lds + PG8_SB(b, h) + boff + n * 2048 + k * 1024); } while (0)
; #define PG8_MMA(ai, bj, At, Bt) do { __builtin_amdgcn_s_setprio(1); _Pragma("unroll") for (int m = 0; m < 4; ++m) _Pragma("unroll") for (int n = 0; n < 2; ++n) _Pragma("unroll") for (int k = 0; k < 2; ++k) \
;         acc[ai][bj][m][n] = __builtin_amdgcn_mfma_f32_16x16x32_bf16(Bt[n][k], At[m][k], acc[ai][bj][m][n], 0, 0, 0); __builtin_amdgcn_s_setprio(0); } while (0)
; #define PG8_WAIT_V(n) asm volatile("s_waitcnt vmcnt(" #n ")" ::: "memory")
; #define PG8_WAIT_L(n) asm volatile("s_waitcnt lgkmcnt(" #n ")" ::: "memory")
; #define PG8_BAR __builtin_amdgcn_s_barrier()
; template <class Epi, class Sched, bool ALIGN_EPI = false, bool SP2 = false>
; __device__ __forceinline__ void gemm_phase(PG8_LAS unsigned char* lds, const Gemm g, const Sched& S, const Epi& E) {
;     ...
;             const char* a1 = cA + (size_t)(t + 1) * kstep;
;             const char* a2 = last ? nA : cA + (size_t)(t + 2) * kstep; const char* b2 = last ? nB : cB + (size_t)(t + 2) * kstep;
;             const char* a3 = a2 + kstep; const char* b3 = b2 + kstep;
;             if (last && has_next) S.a_ready(nxt);
;             if constexpr (SP2) {
;             PG8_LDB(B0, 0, 0); PG8_LDB(B1, 0, 1); PG8_SCHED; PG8_LDA(At, 0, 0); PG8_STAGE(PG8_SA(1, 1), a1 + hstep, voffA);
;             PG8_WAIT_V(8); PG8_WAIT_L(0); PG8_BAR; PG8_MMA(0, 0, At, B0); PG8_MMA(0, 1, At, B1); PG8_BAR; PG8_SCHED;
;             PG8_LDA(At, 0, 1); PG8_STAGE(PG8_SB(0, 0), b2, voffB); PG8_STAGE(PG8_SB(0, 1), b2 + hstep, voffB); PG8_STAGE(PG8_SA(0, 0), a2, voffA);
;             PG8_WAIT_V(8); PG8_WAIT_L(0); PG8_BAR; PG8_MMA(1, 0, At, B0); PG8_MMA(1, 1, At, B1); PG8_BAR; PG8_SCHED;
.Lprio_done_563:
.LBB0_563:
	s_add_u32 s18, s0, 0xfff80080
	s_addc_u32 s19, s1, -1
	s_add_i32 s64, 0, 0x10000
	s_cmp_eq_u32 s63, 28
	s_cselect_b32 s27, s39, s19
	s_cselect_b32 s26, s59, s18
	s_cselect_b32 s19, s37, s62
	s_cselect_b32 s18, s60, s61
	s_add_i32 s66, 0, 0x14000
	v_add_u32_e32 v144, s64, v167
	v_add_u32_e32 v170, s66, v167
	ds_read_b128 v[132:135], v144
	ds_read_b128 v[136:139], v144 offset:1024
	ds_read_b128 v[140:143], v144 offset:2048
	ds_read_b128 v[144:147], v144 offset:3072
	ds_read_b128 v[158:161], v170
	ds_read_b128 v[162:165], v170 offset:1024
	ds_read_b128 v[184:187], v170 offset:2048
	ds_read_b128 v[188:191], v170 offset:3072
	v_lshl_add_u64 v[170:171], s[0:1], 0, v[156:157]
	s_add_i32 m0, s49, 0xc000
	ds_read_b128 v[192:195], v169
	ds_read_b128 v[196:199], v169 offset:1024
	ds_read_b128 v[200:203], v169 offset:2048
	ds_read_b128 v[204:207], v169 offset:3072
	ds_read_b128 v[208:211], v169 offset:4096
	ds_read_b128 v[212:215], v169 offset:5120
	ds_read_b128 v[216:219], v169 offset:6144
	ds_read_b128 v[220:223], v169 offset:7168
	global_load_lds_dwordx4 v[170:171], off
	v_lshl_add_u64 v[170:171], s[0:1], 0, v[154:155]
	s_add_i32 m0, s49, 0xe000
	s_nop 0
	global_load_lds_dwordx4 v[170:171], off
	s_waitcnt vmcnt(8)
	s_waitcnt lgkmcnt(0)
	s_barrier
	s_waitcnt lgkmcnt(0)
	v_mfma_f32_16x16x32_bf16 v[128:131], v[132:135], v[192:195], v[128:131]
	v_mfma_f32_16x16x32_bf16 v[124:127], v[140:143], v[192:195], v[124:127]
	v_mfma_f32_16x16x32_bf16 v[112:115], v[132:135], v[200:203], v[112:115]
	v_mfma_f32_16x16x32_bf16 v[108:111], v[140:143], v[200:203], v[108:111]
	v_mfma_f32_16x16x32_bf16 v[96:99], v[132:135], v[208:211], v[96:99]
	v_mfma_f32_16x16x32_bf16 v[92:95], v[140:143], v[208:211], v[92:95]
	v_mfma_f32_16x16x32_bf16 v[80:83], v[132:135], v[216:219], v[80:83]
	v_mfma_f32_16x16x32_bf16 v[76:79], v[140:143], v[216:219], v[76:79]
	v_mfma_f32_16x16x32_bf16 v[128:131], v[136:139], v[196:199], v[128:131]
	v_mfma_f32_16x16x32_bf16 v[124:127], v[144:147], v[196:199], v[124:127]
	v_mfma_f32_16x16x32_bf16 v[112:115], v[136:139], v[204:207], v[112:115]
	v_mfma_f32_16x16x32_bf16 v[108:111], v[144:147], v[204:207], v[108:111]
	v_mfma_f32_16x16x32_bf16 v[96:99], v[136:139], v[212:215], v[96:99]
	v_mfma_f32_16x16x32_bf16 v[92:95], v[144:147], v[212:215], v[92:95]
	v_mfma_f32_16x16x32_bf16 v[80:83], v[136:139], v[220:223], v[80:83]
	v_mfma_f32_16x16x32_bf16 v[76:79], v[144:147], v[220:223], v[76:79]
	v_mfma_f32_16x16x32_bf16 v[120:123], v[158:161], v[192:195], v[120:123]
	v_mfma_f32_16x16x32_bf16 v[116:119], v[184:187], v[192:195], v[116:119]
	v_mfma_f32_16x16x32_bf16 v[104:107], v[158:161], v[200:203], v[104:107]
	v_mfma_f32_16x16x32_bf16 v[100:103], v[184:187], v[200:203], v[100:103]
	v_mfma_f32_16x16x32_bf16 v[88:91], v[158:161], v[208:211], v[88:91]
	v_mfma_f32_16x16x32_bf16 v[84:87], v[184:187], v[208:211], v[84:87]
	v_mfma_f32_16x16x32_bf16 v[72:75], v[158:161], v[216:219], v[72:75]
	v_mfma_f32_16x16x32_bf16 v[68:71], v[184:187], v[216:219], v[68:71]
	v_mfma_f32_16x16x32_bf16 v[120:123], v[162:165], v[196:199], v[120:123]
	v_mfma_f32_16x16x32_bf16 v[116:119], v[188:191], v[196:199], v[116:119]
	v_mfma_f32_16x16x32_bf16 v[104:107], v[162:165], v[204:207], v[104:107]
	v_mfma_f32_16x16x32_bf16 v[100:103], v[188:191], v[204:207], v[100:103]
	v_mfma_f32_16x16x32_bf16 v[88:91], v[162:165], v[212:215], v[88:91]
	v_mfma_f32_16x16x32_bf16 v[84:87], v[188:191], v[212:215], v[84:87]
	v_mfma_f32_16x16x32_bf16 v[72:75], v[162:165], v[220:223], v[72:75]
	v_mfma_f32_16x16x32_bf16 v[68:71], v[188:191], v[220:223], v[68:71]
	s_barrier
	s_add_i32 s64, s64, s48
	v_lshl_add_u64 v[170:171], s[18:19], 0, v[174:175]
	s_mov_b32 m0, s64
	global_load_lds_dwordx4 v[170:171], off
	s_add_i32 m0, s64, 0x2000
	s_add_u32 s64, s18, 0x80000
	v_lshl_add_u64 v[224:225], s[18:19], 0, v[148:149]
	s_addc_u32 s65, s19, 0
	s_add_i32 s66, s66, s48
	global_load_lds_dwordx4 v[224:225], off
	v_lshl_add_u64 v[226:227], s[64:65], 0, v[174:175]
	s_mov_b32 m0, s66
	v_lshl_add_u64 v[228:229], s[26:27], 0, v[150:151]
	global_load_lds_dwordx4 v[226:227], off
	v_lshl_add_u64 v[226:227], s[64:65], 0, v[148:149]
	s_add_i32 m0, s66, 0x2000
	s_nop 0
	global_load_lds_dwordx4 v[226:227], off
	v_lshl_add_u64 v[226:227], s[26:27], 0, v[152:153]
	s_mov_b32 m0, s49
	s_nop 0
	global_load_lds_dwordx4 v[226:227], off
	s_mov_b32 m0, s50
	s_nop 0
	global_load_lds_dwordx4 v[228:229], off
	ds_read_b128 v[192:195], v169 offset:16384
	ds_read_b128 v[196:199], v169 offset:17408
	ds_read_b128 v[200:203], v169 offset:18432
	ds_read_b128 v[204:207], v169 offset:19456
	ds_read_b128 v[208:211], v169 offset:20480
	ds_read_b128 v[212:215], v169 offset:21504
	ds_read_b128 v[216:219], v169 offset:22528
	ds_read_b128 v[220:223], v169 offset:23552
	s_waitcnt vmcnt(8)
	s_waitcnt lgkmcnt(0)
	s_barrier
; #define PG8_STAGE(bufoff, gbase, voff) do { _Pragma("unroll") for (int _i = 0; _i < 2; ++_i) \
;         __builtin_amdgcn_global_load_lds((const unsigned*)((const char*)(gbase) + (voff)[_i]), (PG8_LAS unsigned*)(lds + (bufoff) + ldsw + _i * 8192), 16, 0, 0); } while (0)
; #define PG8_LDA(dst, b, h) do { _Pragma("unroll") for (int m = 0; m < 4; ++m) _Pragma("unroll") for (int k = 0; k < 2; ++k) dst[m][k] = *(const PG8_LAS bf16x8*)(lds + PG8_SA(b, h) + aoff + m * 2048 + k * 1024); } while (0)
; #define PG8_LDB(dst, b, h) do { _Pragma("unroll") for (int n = 0; n < 2; ++n) _Pragma("unroll") for (int k = 0; k < 2; ++k) dst[n][k] = *(const PG8_LAS bf16x8*)(lds + PG8_SB(b, h) + boff + n * 2048 + k * 1024); } while (0)
; #define PG8_MMA(ai, bj, At, Bt) do { __builtin_amdgcn_s_setprio(1); _Pragma("unroll") for (int m = 0; m < 4; ++m) _Pragma("unroll") for (int n = 0; n < 2; ++n) _Pragma("unroll") for (int k = 0; k < 2; ++k) \
;         acc[ai][bj][m][n] = __builtin_amdgcn_mfma_f32_16x16x32_bf16(Bt[n][k], At[m][k], acc[ai][bj][m][n], 0, 0, 0); __builtin_amdgcn_s_setprio(0); } while (0)
; #define PG8_WAIT_V(n) asm volatile("s_waitcnt vmcnt(" #n ")" ::: "memory")
; #define PG8_WAIT_L(n) asm volatile("s_waitcnt lgkmcnt(" #n ")" ::: "memory")
; #define PG8_BAR __builtin_amdgcn_s_barrier()
; #define PG8_SCHED __builtin_amdgcn_sched_barrier(0)
; template <class Epi, class Sched, bool ALIGN_EPI = false, bool SP2 = false>
; __device__ __forceinline__ void gemm_phase(PG8_LAS unsigned char* lds, const Gemm g, const Sched& S, const Epi& E) {
;     ...
;             PG8_LDA(At, 0, 1); PG8_STAGE(PG8_SB(0, 0), b2, voffB); PG8_STAGE(PG8_SB(0, 1), b2 + hstep, voffB); PG8_STAGE(PG8_SA(0, 0), a2, voffA);
;             PG8_WAIT_V(8); PG8_WAIT_L(0); PG8_BAR; PG8_MMA(1, 0, At, B0); PG8_MMA(1, 1, At, B1); PG8_BAR; PG8_SCHED;
;             PG8_LDB(B0, 1, 0); PG8_LDB(B1, 1, 1); PG8_SCHED; PG8_LDA(At, 1, 0); PG8_STAGE(PG8_SA(0, 1), a2 + hstep, voffA);
;             PG8_WAIT_V(8); PG8_WAIT_L(0); PG8_BAR; PG8_MMA(0, 0, At, B0); PG8_MMA(0, 1, At, B1); PG8_BAR; PG8_SCHED;
	s_waitcnt lgkmcnt(0)
	v_mfma_f32_16x16x32_bf16 v[64:67], v[132:135], v[192:195], v[64:67]
	v_mfma_f32_16x16x32_bf16 v[60:63], v[140:143], v[192:195], v[60:63]
	v_mfma_f32_16x16x32_bf16 v[48:51], v[132:135], v[200:203], v[48:51]
	v_mfma_f32_16x16x32_bf16 v[44:47], v[140:143], v[200:203], v[44:47]
	v_mfma_f32_16x16x32_bf16 v[32:35], v[132:135], v[208:211], v[32:35]
	v_mfma_f32_16x16x32_bf16 v[28:31], v[140:143], v[208:211], v[28:31]
	v_mfma_f32_16x16x32_bf16 v[16:19], v[132:135], v[216:219], v[16:19]
	v_mfma_f32_16x16x32_bf16 v[12:15], v[140:143], v[216:219], v[12:15]
	v_mfma_f32_16x16x32_bf16 v[64:67], v[136:139], v[196:199], v[64:67]
	v_mfma_f32_16x16x32_bf16 v[60:63], v[144:147], v[196:199], v[60:63]
	v_mfma_f32_16x16x32_bf16 v[48:51], v[136:139], v[204:207], v[48:51]
	v_mfma_f32_16x16x32_bf16 v[44:47], v[144:147], v[204:207], v[44:47]
	v_mfma_f32_16x16x32_bf16 v[32:35], v[136:139], v[212:215], v[32:35]
	v_mfma_f32_16x16x32_bf16 v[28:31], v[144:147], v[212:215], v[28:31]
	v_mfma_f32_16x16x32_bf16 v[16:19], v[136:139], v[220:223], v[16:19]
	v_mfma_f32_16x16x32_bf16 v[12:15], v[144:147], v[220:223], v[12:15]
	v_mfma_f32_16x16x32_bf16 v[56:59], v[158:161], v[192:195], v[56:59]
	v_mfma_f32_16x16x32_bf16 v[52:55], v[184:187], v[192:195], v[52:55]
	v_mfma_f32_16x16x32_bf16 v[40:43], v[158:161], v[200:203], v[40:43]
	v_mfma_f32_16x16x32_bf16 v[36:39], v[184:187], v[200:203], v[36:39]
	v_mfma_f32_16x16x32_bf16 v[24:27], v[158:161], v[208:211], v[24:27]
	v_mfma_f32_16x16x32_bf16 v[20:23], v[184:187], v[208:211], v[20:23]
	v_mfma_f32_16x16x32_bf16 v[8:11], v[158:161], v[216:219], v[8:11]
	v_mfma_f32_16x16x32_bf16 v[4:7], v[184:187], v[216:219], v[4:7]
	v_mfma_f32_16x16x32_bf16 v[56:59], v[162:165], v[196:199], v[56:59]
	v_mfma_f32_16x16x32_bf16 v[52:55], v[188:191], v[196:199], v[52:55]
	v_mfma_f32_16x16x32_bf16 v[40:43], v[162:165], v[204:207], v[40:43]
	v_mfma_f32_16x16x32_bf16 v[36:39], v[188:191], v[204:207], v[36:39]
	v_mfma_f32_16x16x32_bf16 v[24:27], v[162:165], v[212:215], v[24:27]
	v_mfma_f32_16x16x32_bf16 v[20:23], v[188:191], v[212:215], v[20:23]
	v_mfma_f32_16x16x32_bf16 v[8:11], v[162:165], v[220:223], v[8:11]
	v_mfma_f32_16x16x32_bf16 v[4:7], v[188:191], v[220:223], v[4:7]
	s_barrier
	s_add_i32 s64, 0, 0x18000
	s_add_i32 s65, 0, 0x1c000
	v_add_u32_e32 v144, s64, v167
	v_add_u32_e32 v179, s65, v167
	ds_read_b128 v[132:135], v144
	ds_read_b128 v[136:139], v144 offset:1024
	ds_read_b128 v[140:143], v144 offset:2048
	ds_read_b128 v[144:147], v144 offset:3072
	ds_read_b128 v[158:161], v179
	ds_read_b128 v[162:165], v179 offset:1024
	ds_read_b128 v[184:187], v179 offset:2048
	ds_read_b128 v[188:191], v179 offset:3072
	s_add_u32 s26, s26, 0x80000
	s_addc_u32 s27, s27, 0
	s_mov_b32 m0, s51
	v_lshl_add_u64 v[230:231], s[26:27], 0, v[152:153]
	ds_read_b128 v[192:195], v169 offset:32768
	ds_read_b128 v[196:199], v169 offset:33792
	ds_read_b128 v[200:203], v169 offset:34816
	ds_read_b128 v[204:207], v169 offset:35840
	ds_read_b128 v[208:211], v169 offset:36864
	ds_read_b128 v[212:215], v169 offset:37888
	ds_read_b128 v[216:219], v169 offset:38912
	ds_read_b128 v[220:223], v169 offset:39936
	global_load_lds_dwordx4 v[230:231], off
	v_lshl_add_u64 v[230:231], s[26:27], 0, v[150:151]
	s_mov_b32 m0, s52
	s_nop 0
	global_load_lds_dwordx4 v[230:231], off
	s_waitcnt vmcnt(8)
	s_waitcnt lgkmcnt(0)
	s_barrier
	s_waitcnt lgkmcnt(0)
	v_mfma_f32_16x16x32_bf16 v[128:131], v[132:135], v[192:195], v[128:131]
	v_mfma_f32_16x16x32_bf16 v[124:127], v[140:143], v[192:195], v[124:127]
	v_mfma_f32_16x16x32_bf16 v[112:115], v[132:135], v[200:203], v[112:115]
	v_mfma_f32_16x16x32_bf16 v[108:111], v[140:143], v[200:203], v[108:111]
	v_mfma_f32_16x16x32_bf16 v[96:99], v[132:135], v[208:211], v[96:99]
	v_mfma_f32_16x16x32_bf16 v[92:95], v[140:143], v[208:211], v[92:95]
	v_mfma_f32_16x16x32_bf16 v[80:83], v[132:135], v[216:219], v[80:83]
	v_mfma_f32_16x16x32_bf16 v[76:79], v[140:143], v[216:219], v[76:79]
	v_mfma_f32_16x16x32_bf16 v[128:131], v[136:139], v[196:199], v[128:131]
	v_mfma_f32_16x16x32_bf16 v[124:127], v[144:147], v[196:199], v[124:127]
	v_mfma_f32_16x16x32_bf16 v[112:115], v[136:139], v[204:207], v[112:115]
	v_mfma_f32_16x16x32_bf16 v[108:111], v[144:147], v[204:207], v[108:111]
	v_mfma_f32_16x16x32_bf16 v[96:99], v[136:139], v[212:215], v[96:99]
	v_mfma_f32_16x16x32_bf16 v[92:95], v[144:147], v[212:215], v[92:95]
	v_mfma_f32_16x16x32_bf16 v[80:83], v[136:139], v[220:223], v[80:83]
	v_mfma_f32_16x16x32_bf16 v[76:79], v[144:147], v[220:223], v[76:79]
	v_mfma_f32_16x16x32_bf16 v[120:123], v[158:161], v[192:195], v[120:123]
	v_mfma_f32_16x16x32_bf16 v[116:119], v[184:187], v[192:195], v[116:119]
	v_mfma_f32_16x16x32_bf16 v[104:107], v[158:161], v[200:203], v[104:107]
	v_mfma_f32_16x16x32_bf16 v[100:103], v[184:187], v[200:203], v[100:103]
	v_mfma_f32_16x16x32_bf16 v[88:91], v[158:161], v[208:211], v[88:91]
	v_mfma_f32_16x16x32_bf16 v[84:87], v[184:187], v[208:211], v[84:87]
	v_mfma_f32_16x16x32_bf16 v[72:75], v[158:161], v[216:219], v[72:75]
	v_mfma_f32_16x16x32_bf16 v[68:71], v[184:187], v[216:219], v[68:71]
	v_mfma_f32_16x16x32_bf16 v[120:123], v[162:165], v[196:199], v[120:123]
	v_mfma_f32_16x16x32_bf16 v[116:119], v[188:191], v[196:199], v[116:119]
	v_mfma_f32_16x16x32_bf16 v[104:107], v[162:165], v[204:207], v[104:107]
	v_mfma_f32_16x16x32_bf16 v[100:103], v[188:191], v[204:207], v[100:103]
	v_mfma_f32_16x16x32_bf16 v[88:91], v[162:165], v[212:215], v[88:91]
	v_mfma_f32_16x16x32_bf16 v[84:87], v[188:191], v[212:215], v[84:87]
	v_mfma_f32_16x16x32_bf16 v[72:75], v[162:165], v[220:223], v[72:75]
	v_mfma_f32_16x16x32_bf16 v[68:71], v[188:191], v[220:223], v[68:71]
	s_barrier
; #define PG8_STAGE(bufoff, gbase, voff) do { _Pragma("unroll") for (int _i = 0; _i < 2; ++_i) \
;         __builtin_amdgcn_global_load_lds((const unsigned*)((const char*)(gbase) + (voff)[_i]), (PG8_LAS unsigned*)(lds + (bufoff) + ldsw + _i * 8192), 16, 0, 0); } while (0)
; #define PG8_LDA(dst, b, h) do { _Pragma("unroll") for (int m = 0; m < 4; ++m) _Pragma("unroll") for (int k = 0; k < 2; ++k) dst[m][k] = *(const PG8_LAS bf16x8*)(lds + PG8_SA(b, h) + aoff + m * 2048 + k * 1024); } while (0)
; #define PG8_MMA(ai, bj, At, Bt) do { __builtin_amdgcn_s_setprio(1); _Pragma("unroll") for (int m = 0; m < 4; ++m) _Pragma("unroll") for (int n = 0; n < 2; ++n) _Pragma("unroll") for (int k = 0; k < 2; ++k) \
;         acc[ai][bj][m][n] = __builtin_amdgcn_mfma_f32_16x16x32_bf16(Bt[n][k], At[m][k], acc[ai][bj][m][n], 0, 0, 0); __builtin_amdgcn_s_setprio(0); } while (0)
; #define PG8_WAIT_V(n) asm volatile("s_waitcnt vmcnt(" #n ")" ::: "memory")
; #define PG8_WAIT_L(n) asm volatile("s_waitcnt lgkmcnt(" #n ")" ::: "memory")
; #define PG8_BAR __builtin_amdgcn_s_barrier()
; #define PG8_SCHED __builtin_amdgcn_sched_barrier(0)
; template <class Epi, class Sched, bool ALIGN_EPI = false, bool SP2 = false>
; __device__ __forceinline__ void gemm_phase(PG8_LAS unsigned char* lds, const Gemm g, const Sched& S, const Epi& E) {
;     ...
;             PG8_LDA(At, 1, 1); PG8_STAGE(PG8_SB(1, 0), b3, voffB); PG8_STAGE(PG8_SB(1, 1), b3 + hstep, voffB); PG8_STAGE(PG8_SA(1, 0), a3, voffA);
;             PG8_WAIT_V(8); PG8_WAIT_L(0); PG8_BAR; PG8_MMA(1, 0, At, B0); PG8_MMA(1, 1, At, B1); PG8_BAR; PG8_SCHED;
;     ...
;         if constexpr (ALIGN_EPI) { if (wr == 0) PG8_BAR; }
	s_add_i32 s26, s64, s48
	v_lshl_add_u64 v[170:171], v[170:171], 0, s[10:11]
	s_mov_b32 m0, s26
	global_load_lds_dwordx4 v[170:171], off
	s_add_i32 m0, s26, 0x2000
	s_add_u32 s18, s18, 0x80080
	v_lshl_add_u64 v[170:171], v[224:225], 0, s[10:11]
	s_addc_u32 s19, s19, 0
	s_add_i32 s26, s65, s48
	global_load_lds_dwordx4 v[170:171], off
	v_lshl_add_u64 v[170:171], s[18:19], 0, v[174:175]
	s_mov_b32 m0, s26
	s_nop 0
	global_load_lds_dwordx4 v[170:171], off
	v_lshl_add_u64 v[170:171], s[18:19], 0, v[148:149]
	s_add_i32 m0, s26, 0x2000
	s_nop 0
	global_load_lds_dwordx4 v[170:171], off
	v_lshl_add_u64 v[170:171], v[226:227], 0, s[10:11]
	s_mov_b32 m0, s54
	s_nop 0
	global_load_lds_dwordx4 v[170:171], off
	v_lshl_add_u64 v[170:171], v[228:229], 0, s[10:11]
	s_mov_b32 m0, s55
	s_nop 0
	global_load_lds_dwordx4 v[170:171], off
	ds_read_b128 v[192:195], v169 offset:49152
	ds_read_b128 v[196:199], v169 offset:50176
	ds_read_b128 v[200:203], v169 offset:51200
	ds_read_b128 v[204:207], v169 offset:52224
	ds_read_b128 v[208:211], v169 offset:53248
	ds_read_b128 v[212:215], v169 offset:54272
	ds_read_b128 v[216:219], v169 offset:55296
	ds_read_b128 v[220:223], v169 offset:56320
	s_waitcnt vmcnt(8)
	s_waitcnt lgkmcnt(0)
	s_barrier
	s_waitcnt lgkmcnt(0)
	v_mfma_f32_16x16x32_bf16 v[64:67], v[132:135], v[192:195], v[64:67]
	v_mfma_f32_16x16x32_bf16 v[60:63], v[140:143], v[192:195], v[60:63]
	v_mfma_f32_16x16x32_bf16 v[48:51], v[132:135], v[200:203], v[48:51]
	v_mfma_f32_16x16x32_bf16 v[44:47], v[140:143], v[200:203], v[44:47]
	v_mfma_f32_16x16x32_bf16 v[32:35], v[132:135], v[208:211], v[32:35]
	v_mfma_f32_16x16x32_bf16 v[28:31], v[140:143], v[208:211], v[28:31]
	v_mfma_f32_16x16x32_bf16 v[16:19], v[132:135], v[216:219], v[16:19]
	v_mfma_f32_16x16x32_bf16 v[12:15], v[140:143], v[216:219], v[12:15]
	v_mfma_f32_16x16x32_bf16 v[64:67], v[136:139], v[196:199], v[64:67]
	v_mfma_f32_16x16x32_bf16 v[60:63], v[144:147], v[196:199], v[60:63]
	v_mfma_f32_16x16x32_bf16 v[48:51], v[136:139], v[204:207], v[48:51]
	v_mfma_f32_16x16x32_bf16 v[44:47], v[144:147], v[204:207], v[44:47]
	v_mfma_f32_16x16x32_bf16 v[32:35], v[136:139], v[212:215], v[32:35]
	v_mfma_f32_16x16x32_bf16 v[28:31], v[144:147], v[212:215], v[28:31]
	v_mfma_f32_16x16x32_bf16 v[16:19], v[136:139], v[220:223], v[16:19]
	v_mfma_f32_16x16x32_bf16 v[12:15], v[144:147], v[220:223], v[12:15]
	v_mfma_f32_16x16x32_bf16 v[56:59], v[158:161], v[192:195], v[56:59]
	v_mfma_f32_16x16x32_bf16 v[52:55], v[184:187], v[192:195], v[52:55]
	v_mfma_f32_16x16x32_bf16 v[40:43], v[158:161], v[200:203], v[40:43]
	v_mfma_f32_16x16x32_bf16 v[36:39], v[184:187], v[200:203], v[36:39]
	v_mfma_f32_16x16x32_bf16 v[24:27], v[158:161], v[208:211], v[24:27]
	v_mfma_f32_16x16x32_bf16 v[20:23], v[184:187], v[208:211], v[20:23]
	v_mfma_f32_16x16x32_bf16 v[8:11], v[158:161], v[216:219], v[8:11]
	v_mfma_f32_16x16x32_bf16 v[4:7], v[184:187], v[216:219], v[4:7]
	v_mfma_f32_16x16x32_bf16 v[56:59], v[162:165], v[196:199], v[56:59]
	v_mfma_f32_16x16x32_bf16 v[52:55], v[188:191], v[196:199], v[52:55]
	v_mfma_f32_16x16x32_bf16 v[40:43], v[162:165], v[204:207], v[40:43]
	v_mfma_f32_16x16x32_bf16 v[36:39], v[188:191], v[204:207], v[36:39]
	v_mfma_f32_16x16x32_bf16 v[24:27], v[162:165], v[212:215], v[24:27]
	v_mfma_f32_16x16x32_bf16 v[20:23], v[188:191], v[212:215], v[20:23]
	v_mfma_f32_16x16x32_bf16 v[8:11], v[162:165], v[220:223], v[8:11]
	v_mfma_f32_16x16x32_bf16 v[4:7], v[188:191], v[220:223], v[4:7]
	s_barrier
	s_add_i32 s63, s63, 2
	s_add_u32 s61, s61, 0x100
	s_addc_u32 s62, s62, 0
	s_add_u32 s0, s0, 0x100
	s_addc_u32 s1, s1, 0
	s_cmp_gt_u32 s63, 29
	s_cbranch_scc0 .LBB0_563
	s_and_b64 vcc, exec, s[34:35]
	s_cbranch_vccz .LBB0_566
	s_barrier

; #define PG8_STAGE(bufoff, gbase, voff) do { _Pragma("unroll") for (int _i = 0; _i < 2; ++_i) \
;         __builtin_amdgcn_global_load_lds((const unsigned*)((const char*)(gbase) + (voff)[_i]), (PG8_LAS unsigned*)(lds + (bufoff) + ldsw + _i * 8192), 16, 0, 0); } while (0)
; #define PG8_LDA(dst, b, h) do { _Pragma("unroll") for (int m = 0; m < 4; ++m) _Pragma("unroll") for (int k = 0; k < 2; ++k) dst[m][k] = *(const PG8_LAS bf16x8*)(lds + PG8_SA(b, h) + aoff + m * 2048 + k * 1024); } while (0)
; #define PG8_LDB(dst, b, h) do { _Pragma("unroll") for (int n = 0; n < 2; ++n) _Pragma("unroll") for (int k = 0; k < 2; ++k) dst[n][k] = *(const PG8_LAS bf16x8*)(lds + PG8_SB(b, h) + boff + n * 2048 + k * 1024); } while (0)
; #define PG8_MMA(ai, bj, At, Bt) do { __builtin_amdgcn_s_setprio(1); _Pragma("unroll") for (int m = 0; m < 4; ++m) _Pragma("unroll") for (int n = 0; n < 2; ++n) _Pragma("unroll") for (int k = 0; k < 2; ++k) \
;         acc[ai][bj][m][n] = __builtin_amdgcn_mfma_f32_16x16x32_bf16(Bt[n][k], At[m][k], acc[ai][bj][m][n], 0, 0, 0); __builtin_amdgcn_s_setprio(0); } while (0)
; #define PG8_WAIT_V(n) asm volatile("s_waitcnt vmcnt(" #n ")" ::: "memory")
; #define PG8_WAIT_L(n) asm volatile("s_waitcnt lgkmcnt(" #n ")" ::: "memory")
; #define PG8_BAR __builtin_amdgcn_s_barrier()
; template <class Epi, class Sched, bool ALIGN_EPI = false, bool SP2 = false>
; __device__ __forceinline__ void gemm_phase(PG8_LAS unsigned char* lds, const Gemm g, const Sched& S, const Epi& E) {
;     ...
;             const char* a1 = cA + (size_t)(t + 1) * kstep;
;             const char* a2 = last ? nA : cA + (size_t)(t + 2) * kstep; const char* b2 = last ? nB : cB + (size_t)(t + 2) * kstep;
;             const char* a3 = a2 + kstep; const char* b3 = b2 + kstep;
;             if (last && has_next) S.a_ready(nxt);
;             if constexpr (SP2) {
;             PG8_LDB(B0, 0, 0); PG8_LDB(B1, 0, 1); PG8_SCHED; PG8_LDA(At, 0, 0); PG8_STAGE(PG8_SA(1, 1), a1 + hstep, voffA);
;             PG8_WAIT_V(8); PG8_WAIT_L(0); PG8_BAR; PG8_MMA(0, 0, At, B0); PG8_MMA(0, 1, At, B1); PG8_BAR; PG8_SCHED;
;             PG8_LDA(At, 0, 1); PG8_STAGE(PG8_SB(0, 0), b2, voffB); PG8_STAGE(PG8_SB(0, 1), b2 + hstep, voffB); PG8_STAGE(PG8_SA(0, 0), a2, voffA);
;             PG8_WAIT_V(8); PG8_WAIT_L(0); PG8_BAR; PG8_MMA(1, 0, At, B0); PG8_MMA(1, 1, At, B1); PG8_BAR; PG8_SCHED;
.Lprio_done_660:
.LBB0_660:
	s_add_u32 s14, s0, 0xfff80080
	s_addc_u32 s15, s1, -1
	s_add_i32 s46, 0, 0x10000
	s_cmp_eq_u32 s45, 28
	s_cselect_b32 s17, s23, s15
	s_cselect_b32 s16, s24, s14
	s_cselect_b32 s15, s25, s44
	s_cselect_b32 s14, s42, s43
	s_add_i32 s63, 0, 0x14000
	v_add_u32_e32 v48, s46, v243
	v_add_u32_e32 v96, s63, v243
	ds_read_b128 v[36:39], v48
	ds_read_b128 v[40:43], v48 offset:1024
	ds_read_b128 v[44:47], v48 offset:2048
	ds_read_b128 v[48:51], v48 offset:3072
	ds_read_b128 v[76:79], v96
	ds_read_b128 v[80:83], v96 offset:1024
	ds_read_b128 v[84:87], v96 offset:2048
	ds_read_b128 v[96:99], v96 offset:3072
	v_lshl_add_u64 v[224:225], s[0:1], 0, v[198:199]
	s_add_i32 m0, s29, 0xc000
	ds_read_b128 v[164:167], v249
	ds_read_b128 v[168:171], v249 offset:1024
	ds_read_b128 v[200:203], v249 offset:2048
	ds_read_b128 v[204:207], v249 offset:3072
	ds_read_b128 v[208:211], v249 offset:4096
	ds_read_b128 v[212:215], v249 offset:5120
	ds_read_b128 v[216:219], v249 offset:6144
	ds_read_b128 v[220:223], v249 offset:7168
	global_load_lds_dwordx4 v[224:225], off
	v_lshl_add_u64 v[224:225], s[0:1], 0, v[196:197]
	s_add_i32 m0, s29, 0xe000
	s_nop 0
	global_load_lds_dwordx4 v[224:225], off
	s_waitcnt vmcnt(8)
	s_waitcnt lgkmcnt(0)
	s_barrier
	s_waitcnt lgkmcnt(0)
	v_mfma_f32_16x16x32_bf16 v[152:155], v[36:39], v[164:167], v[152:155]
	v_mfma_f32_16x16x32_bf16 v[148:151], v[44:47], v[164:167], v[148:151]
	v_mfma_f32_16x16x32_bf16 v[136:139], v[36:39], v[200:203], v[136:139]
	v_mfma_f32_16x16x32_bf16 v[132:135], v[44:47], v[200:203], v[132:135]
	v_mfma_f32_16x16x32_bf16 v[128:131], v[36:39], v[208:211], v[128:131]
	v_mfma_f32_16x16x32_bf16 v[124:127], v[44:47], v[208:211], v[124:127]
	v_mfma_f32_16x16x32_bf16 v[160:163], v[36:39], v[216:219], v[160:163]
	v_mfma_f32_16x16x32_bf16 v[156:159], v[44:47], v[216:219], v[156:159]
	v_mfma_f32_16x16x32_bf16 v[152:155], v[40:43], v[168:171], v[152:155]
	v_mfma_f32_16x16x32_bf16 v[148:151], v[48:51], v[168:171], v[148:151]
	v_mfma_f32_16x16x32_bf16 v[136:139], v[40:43], v[204:207], v[136:139]
	v_mfma_f32_16x16x32_bf16 v[132:135], v[48:51], v[204:207], v[132:135]
	v_mfma_f32_16x16x32_bf16 v[128:131], v[40:43], v[212:215], v[128:131]
	v_mfma_f32_16x16x32_bf16 v[124:127], v[48:51], v[212:215], v[124:127]
	v_mfma_f32_16x16x32_bf16 v[160:163], v[40:43], v[220:223], v[160:163]
	v_mfma_f32_16x16x32_bf16 v[156:159], v[48:51], v[220:223], v[156:159]
	v_mfma_f32_16x16x32_bf16 v[144:147], v[76:79], v[164:167], v[144:147]
	v_mfma_f32_16x16x32_bf16 v[140:143], v[84:87], v[164:167], v[140:143]
	v_mfma_f32_16x16x32_bf16 v[120:123], v[76:79], v[200:203], v[120:123]
	v_mfma_f32_16x16x32_bf16 v[116:119], v[84:87], v[200:203], v[116:119]
	v_mfma_f32_16x16x32_bf16 v[112:115], v[76:79], v[208:211], v[112:115]
	v_mfma_f32_16x16x32_bf16 v[108:111], v[84:87], v[208:211], v[108:111]
	v_mfma_f32_16x16x32_bf16 v[104:107], v[76:79], v[216:219], v[104:107]
	v_mfma_f32_16x16x32_bf16 v[100:103], v[84:87], v[216:219], v[100:103]
	v_mfma_f32_16x16x32_bf16 v[144:147], v[80:83], v[168:171], v[144:147]
	v_mfma_f32_16x16x32_bf16 v[140:143], v[96:99], v[168:171], v[140:143]
	v_mfma_f32_16x16x32_bf16 v[120:123], v[80:83], v[204:207], v[120:123]
	v_mfma_f32_16x16x32_bf16 v[116:119], v[96:99], v[204:207], v[116:119]
	v_mfma_f32_16x16x32_bf16 v[112:115], v[80:83], v[212:215], v[112:115]
	v_mfma_f32_16x16x32_bf16 v[108:111], v[96:99], v[212:215], v[108:111]
	v_mfma_f32_16x16x32_bf16 v[104:107], v[80:83], v[220:223], v[104:107]
	v_mfma_f32_16x16x32_bf16 v[100:103], v[96:99], v[220:223], v[100:103]
	s_barrier
	s_add_i32 s46, s46, s28
	v_lshl_add_u64 v[232:233], s[14:15], 0, v[188:189]
	s_mov_b32 m0, s46
	global_load_lds_dwordx4 v[232:233], off
	s_add_i32 m0, s46, 0x2000
	s_add_u32 s46, s14, 0x80000
	v_lshl_add_u64 v[234:235], s[14:15], 0, v[184:185]
	s_addc_u32 s47, s15, 0
	s_add_i32 s63, s63, s28
	global_load_lds_dwordx4 v[234:235], off
	v_lshl_add_u64 v[224:225], s[46:47], 0, v[188:189]
	s_mov_b32 m0, s63
	v_lshl_add_u64 v[236:237], s[16:17], 0, v[190:191]
	global_load_lds_dwordx4 v[224:225], off
	v_lshl_add_u64 v[224:225], s[46:47], 0, v[184:185]
	s_add_i32 m0, s63, 0x2000
	v_lshl_add_u64 v[250:251], s[16:17], 0, v[186:187]
	global_load_lds_dwordx4 v[224:225], off
	s_mov_b32 m0, s29
	s_nop 0
	global_load_lds_dwordx4 v[236:237], off
	s_mov_b32 m0, s30
	s_nop 0
	global_load_lds_dwordx4 v[250:251], off
	ds_read_b128 v[164:167], v249 offset:16384
	ds_read_b128 v[168:171], v249 offset:17408
	ds_read_b128 v[200:203], v249 offset:18432
	ds_read_b128 v[204:207], v249 offset:19456
	ds_read_b128 v[208:211], v249 offset:20480
	ds_read_b128 v[212:215], v249 offset:21504
	ds_read_b128 v[216:219], v249 offset:22528
	ds_read_b128 v[220:223], v249 offset:23552
	s_waitcnt vmcnt(8)
	s_waitcnt lgkmcnt(0)
	s_barrier
; #define PG8_STAGE(bufoff, gbase, voff) do { _Pragma("unroll") for (int _i = 0; _i < 2; ++_i) \
;         __builtin_amdgcn_global_load_lds((const unsigned*)((const char*)(gbase) + (voff)[_i]), (PG8_LAS unsigned*)(lds + (bufoff) + ldsw + _i * 8192), 16, 0, 0); } while (0)
; #define PG8_LDA(dst, b, h) do { _Pragma("unroll") for (int m = 0; m < 4; ++m) _Pragma("unroll") for (int k = 0; k < 2; ++k) dst[m][k] = *(const PG8_LAS bf16x8*)(lds + PG8_SA(b, h) + aoff + m * 2048 + k * 1024); } while (0)
; #define PG8_LDB(dst, b, h) do { _Pragma("unroll") for (int n = 0; n < 2; ++n) _Pragma("unroll") for (int k = 0; k < 2; ++k) dst[n][k] = *(const PG8_LAS bf16x8*)(lds + PG8_SB(b, h) + boff + n * 2048 + k * 1024); } while (0)
; #define PG8_MMA(ai, bj, At, Bt) do { __builtin_amdgcn_s_setprio(1); _Pragma("unroll") for (int m = 0; m < 4; ++m) _Pragma("unroll") for (int n = 0; n < 2; ++n) _Pragma("unroll") for (int k = 0; k < 2; ++k) \
;         acc[ai][bj][m][n] = __builtin_amdgcn_mfma_f32_16x16x32_bf16(Bt[n][k], At[m][k], acc[ai][bj][m][n], 0, 0, 0); __builtin_amdgcn_s_setprio(0); } while (0)
; #define PG8_WAIT_V(n) asm volatile("s_waitcnt vmcnt(" #n ")" ::: "memory")
; #define PG8_WAIT_L(n) asm volatile("s_waitcnt lgkmcnt(" #n ")" ::: "memory")
; #define PG8_BAR __builtin_amdgcn_s_barrier()
; #define PG8_SCHED __builtin_amdgcn_sched_barrier(0)
; template <class Epi, class Sched, bool ALIGN_EPI = false, bool SP2 = false>
; __device__ __forceinline__ void gemm_phase(PG8_LAS unsigned char* lds, const Gemm g, const Sched& S, const Epi& E) {
;     ...
;             PG8_LDA(At, 0, 1); PG8_STAGE(PG8_SB(0, 0), b2, voffB); PG8_STAGE(PG8_SB(0, 1), b2 + hstep, voffB); PG8_STAGE(PG8_SA(0, 0), a2, voffA);
;             PG8_WAIT_V(8); PG8_WAIT_L(0); PG8_BAR; PG8_MMA(1, 0, At, B0); PG8_MMA(1, 1, At, B1); PG8_BAR; PG8_SCHED;
;             PG8_LDB(B0, 1, 0); PG8_LDB(B1, 1, 1); PG8_SCHED; PG8_LDA(At, 1, 0); PG8_STAGE(PG8_SA(0, 1), a2 + hstep, voffA);
;             PG8_WAIT_V(8); PG8_WAIT_L(0); PG8_BAR; PG8_MMA(0, 0, At, B0); PG8_MMA(0, 1, At, B1); PG8_BAR; PG8_SCHED;
	s_waitcnt lgkmcnt(0)
	v_mfma_f32_16x16x32_bf16 v[72:75], v[36:39], v[164:167], v[72:75]
	v_mfma_f32_16x16x32_bf16 v[68:71], v[44:47], v[164:167], v[68:71]
	v_mfma_f32_16x16x32_bf16 v[64:67], v[36:39], v[200:203], v[64:67]
	v_mfma_f32_16x16x32_bf16 v[60:63], v[44:47], v[200:203], v[60:63]
	v_mfma_f32_16x16x32_bf16 v[56:59], v[36:39], v[208:211], v[56:59]
	v_mfma_f32_16x16x32_bf16 v[52:55], v[44:47], v[208:211], v[52:55]
	v_mfma_f32_16x16x32_bf16 v[36:39], v[36:39], v[216:219], v[92:95]
	v_mfma_f32_16x16x32_bf16 v[72:75], v[40:43], v[168:171], v[72:75]
	v_mfma_f32_16x16x32_bf16 v[68:71], v[48:51], v[168:171], v[68:71]
	v_mfma_f32_16x16x32_bf16 v[64:67], v[40:43], v[204:207], v[64:67]
	v_mfma_f32_16x16x32_bf16 v[60:63], v[48:51], v[204:207], v[60:63]
	v_mfma_f32_16x16x32_bf16 v[56:59], v[40:43], v[212:215], v[56:59]
	v_mfma_f32_16x16x32_bf16 v[52:55], v[48:51], v[212:215], v[52:55]
	v_mfma_f32_16x16x32_bf16 v[36:39], v[40:43], v[220:223], v[36:39]
	v_mfma_f32_16x16x32_bf16 v[40:43], v[44:47], v[216:219], v[88:91]
	v_mfma_f32_16x16x32_bf16 v[40:43], v[48:51], v[220:223], v[40:43]
	v_mfma_f32_16x16x32_bf16 v[32:35], v[76:79], v[164:167], v[32:35]
	v_mfma_f32_16x16x32_bf16 v[28:31], v[84:87], v[164:167], v[28:31]
	v_mfma_f32_16x16x32_bf16 v[24:27], v[76:79], v[200:203], v[24:27]
	v_mfma_f32_16x16x32_bf16 v[20:23], v[84:87], v[200:203], v[20:23]
	v_mfma_f32_16x16x32_bf16 v[16:19], v[76:79], v[208:211], v[16:19]
	v_mfma_f32_16x16x32_bf16 v[12:15], v[84:87], v[208:211], v[12:15]
	v_mfma_f32_16x16x32_bf16 v[8:11], v[76:79], v[216:219], v[8:11]
	v_mfma_f32_16x16x32_bf16 v[4:7], v[84:87], v[216:219], v[4:7]
	v_mfma_f32_16x16x32_bf16 v[32:35], v[80:83], v[168:171], v[32:35]
	v_mfma_f32_16x16x32_bf16 v[28:31], v[96:99], v[168:171], v[28:31]
	v_mfma_f32_16x16x32_bf16 v[24:27], v[80:83], v[204:207], v[24:27]
	v_mfma_f32_16x16x32_bf16 v[20:23], v[96:99], v[204:207], v[20:23]
	v_mfma_f32_16x16x32_bf16 v[16:19], v[80:83], v[212:215], v[16:19]
	v_mfma_f32_16x16x32_bf16 v[12:15], v[96:99], v[212:215], v[12:15]
	v_mfma_f32_16x16x32_bf16 v[8:11], v[80:83], v[220:223], v[8:11]
	v_mfma_f32_16x16x32_bf16 v[4:7], v[96:99], v[220:223], v[4:7]
	s_barrier
	s_add_i32 s46, 0, 0x18000
	s_add_i32 s47, 0, 0x1c000
	v_add_u32_e32 v80, s46, v243
	v_add_u32_e32 v88, s47, v243
	ds_read_b128 v[44:47], v80
	ds_read_b128 v[48:51], v80 offset:1024
	ds_read_b128 v[76:79], v80 offset:2048
	ds_read_b128 v[80:83], v80 offset:3072
	ds_read_b128 v[84:87], v88
	ds_read_b128 v[96:99], v88 offset:1024
	ds_read_b128 v[164:167], v88 offset:2048
	ds_read_b128 v[168:171], v88 offset:3072
	s_add_u32 s16, s16, 0x80000
	s_addc_u32 s17, s17, 0
	s_mov_b32 m0, s31
	v_lshl_add_u64 v[224:225], s[16:17], 0, v[190:191]
	ds_read_b128 v[88:91], v249 offset:32768
	ds_read_b128 v[92:95], v249 offset:33792
	ds_read_b128 v[200:203], v249 offset:34816
	ds_read_b128 v[204:207], v249 offset:35840
	ds_read_b128 v[208:211], v249 offset:36864
	ds_read_b128 v[212:215], v249 offset:37888
	ds_read_b128 v[216:219], v249 offset:38912
	ds_read_b128 v[220:223], v249 offset:39936
	global_load_lds_dwordx4 v[224:225], off
	v_lshl_add_u64 v[224:225], s[16:17], 0, v[186:187]
	s_mov_b32 m0, s34
	s_nop 0
	global_load_lds_dwordx4 v[224:225], off
	s_waitcnt vmcnt(8)
	s_waitcnt lgkmcnt(0)
	s_barrier
	s_waitcnt lgkmcnt(0)
	v_mfma_f32_16x16x32_bf16 v[152:155], v[44:47], v[88:91], v[152:155]
	v_mfma_f32_16x16x32_bf16 v[148:151], v[76:79], v[88:91], v[148:151]
	v_mfma_f32_16x16x32_bf16 v[136:139], v[44:47], v[200:203], v[136:139]
	v_mfma_f32_16x16x32_bf16 v[132:135], v[76:79], v[200:203], v[132:135]
	v_mfma_f32_16x16x32_bf16 v[128:131], v[44:47], v[208:211], v[128:131]
	v_mfma_f32_16x16x32_bf16 v[124:127], v[76:79], v[208:211], v[124:127]
	v_mfma_f32_16x16x32_bf16 v[160:163], v[44:47], v[216:219], v[160:163]
	v_mfma_f32_16x16x32_bf16 v[156:159], v[76:79], v[216:219], v[156:159]
	v_mfma_f32_16x16x32_bf16 v[152:155], v[48:51], v[92:95], v[152:155]
	v_mfma_f32_16x16x32_bf16 v[148:151], v[80:83], v[92:95], v[148:151]
	v_mfma_f32_16x16x32_bf16 v[136:139], v[48:51], v[204:207], v[136:139]
	v_mfma_f32_16x16x32_bf16 v[132:135], v[80:83], v[204:207], v[132:135]
	v_mfma_f32_16x16x32_bf16 v[128:131], v[48:51], v[212:215], v[128:131]
	v_mfma_f32_16x16x32_bf16 v[124:127], v[80:83], v[212:215], v[124:127]
	v_mfma_f32_16x16x32_bf16 v[160:163], v[48:51], v[220:223], v[160:163]
	v_mfma_f32_16x16x32_bf16 v[156:159], v[80:83], v[220:223], v[156:159]
	v_mfma_f32_16x16x32_bf16 v[144:147], v[84:87], v[88:91], v[144:147]
	v_mfma_f32_16x16x32_bf16 v[88:91], v[164:167], v[88:91], v[140:143]
	v_mfma_f32_16x16x32_bf16 v[140:143], v[168:171], v[92:95], v[88:91]
	v_mfma_f32_16x16x32_bf16 v[88:91], v[84:87], v[200:203], v[120:123]
	v_mfma_f32_16x16x32_bf16 v[120:123], v[96:99], v[204:207], v[88:91]
	v_mfma_f32_16x16x32_bf16 v[88:91], v[164:167], v[200:203], v[116:119]
	v_mfma_f32_16x16x32_bf16 v[116:119], v[168:171], v[204:207], v[88:91]
	v_mfma_f32_16x16x32_bf16 v[88:91], v[84:87], v[208:211], v[112:115]
	v_mfma_f32_16x16x32_bf16 v[112:115], v[96:99], v[212:215], v[88:91]
	v_mfma_f32_16x16x32_bf16 v[88:91], v[164:167], v[208:211], v[108:111]
	v_mfma_f32_16x16x32_bf16 v[108:111], v[168:171], v[212:215], v[88:91]
	v_mfma_f32_16x16x32_bf16 v[88:91], v[84:87], v[216:219], v[104:107]
	v_mfma_f32_16x16x32_bf16 v[104:107], v[96:99], v[220:223], v[88:91]
	v_mfma_f32_16x16x32_bf16 v[88:91], v[164:167], v[216:219], v[100:103]
	v_mfma_f32_16x16x32_bf16 v[144:147], v[96:99], v[92:95], v[144:147]
	v_mfma_f32_16x16x32_bf16 v[100:103], v[168:171], v[220:223], v[88:91]
	s_barrier
; #define PG8_STAGE(bufoff, gbase, voff) do { _Pragma("unroll") for (int _i = 0; _i < 2; ++_i) \
;         __builtin_amdgcn_global_load_lds((const unsigned*)((const char*)(gbase) + (voff)[_i]), (PG8_LAS unsigned*)(lds + (bufoff) + ldsw + _i * 8192), 16, 0, 0); } while (0)
; #define PG8_LDA(dst, b, h) do { _Pragma("unroll") for (int m = 0; m < 4; ++m) _Pragma("unroll") for (int k = 0; k < 2; ++k) dst[m][k] = *(const PG8_LAS bf16x8*)(lds + PG8_SA(b, h) + aoff + m * 2048 + k * 1024); } while (0)
; #define PG8_MMA(ai, bj, At, Bt) do { __builtin_amdgcn_s_setprio(1); _Pragma("unroll") for (int m = 0; m < 4; ++m) _Pragma("unroll") for (int n = 0; n < 2; ++n) _Pragma("unroll") for (int k = 0; k < 2; ++k) \
;         acc[ai][bj][m][n] = __builtin_amdgcn_mfma_f32_16x16x32_bf16(Bt[n][k], At[m][k], acc[ai][bj][m][n], 0, 0, 0); __builtin_amdgcn_s_setprio(0); } while (0)
; #define PG8_WAIT_V(n) asm volatile("s_waitcnt vmcnt(" #n ")" ::: "memory")
; #define PG8_WAIT_L(n) asm volatile("s_waitcnt lgkmcnt(" #n ")" ::: "memory")
; #define PG8_BAR __builtin_amdgcn_s_barrier()
; #define PG8_SCHED __builtin_amdgcn_sched_barrier(0)
; template <class Epi, class Sched, bool ALIGN_EPI = false, bool SP2 = false>
; __device__ __forceinline__ void gemm_phase(PG8_LAS unsigned char* lds, const Gemm g, const Sched& S, const Epi& E) {
;     ...
;             PG8_LDA(At, 1, 1); PG8_STAGE(PG8_SB(1, 0), b3, voffB); PG8_STAGE(PG8_SB(1, 1), b3 + hstep, voffB); PG8_STAGE(PG8_SA(1, 0), a3, voffA);
;             PG8_WAIT_V(8); PG8_WAIT_L(0); PG8_BAR; PG8_MMA(1, 0, At, B0); PG8_MMA(1, 1, At, B1); PG8_BAR; PG8_SCHED;
;     ...
;         if constexpr (ALIGN_EPI) { if (wr == 0) PG8_BAR; }
	s_add_i32 s16, s46, s28
	s_nop 2
	v_lshl_add_u64 v[88:89], v[232:233], 0, s[10:11]
	s_mov_b32 m0, s16
	global_load_lds_dwordx4 v[88:89], off
	s_add_i32 m0, s16, 0x2000
	s_add_u32 s14, s14, 0x80080
	v_lshl_add_u64 v[88:89], v[234:235], 0, s[10:11]
	s_addc_u32 s15, s15, 0
	s_add_i32 s16, s47, s28
	global_load_lds_dwordx4 v[88:89], off
	v_lshl_add_u64 v[88:89], s[14:15], 0, v[188:189]
	s_mov_b32 m0, s16
	s_nop 0
	global_load_lds_dwordx4 v[88:89], off
	v_lshl_add_u64 v[88:89], s[14:15], 0, v[184:185]
	s_add_i32 m0, s16, 0x2000
	s_nop 0
	global_load_lds_dwordx4 v[88:89], off
	v_lshl_add_u64 v[88:89], v[236:237], 0, s[10:11]
	s_mov_b32 m0, s72
	s_nop 0
	global_load_lds_dwordx4 v[88:89], off
	v_lshl_add_u64 v[88:89], v[250:251], 0, s[10:11]
	s_mov_b32 m0, s73
	s_nop 0
	global_load_lds_dwordx4 v[88:89], off
	ds_read_b128 v[200:203], v249 offset:49152
	ds_read_b128 v[204:207], v249 offset:50176
	ds_read_b128 v[208:211], v249 offset:51200
	ds_read_b128 v[212:215], v249 offset:52224
	ds_read_b128 v[216:219], v249 offset:53248
	ds_read_b128 v[220:223], v249 offset:54272
	ds_read_b128 v[224:227], v249 offset:55296
	ds_read_b128 v[228:231], v249 offset:56320
	s_waitcnt vmcnt(8)
	s_waitcnt lgkmcnt(0)
	s_barrier
	s_waitcnt lgkmcnt(0)
	v_mfma_f32_16x16x32_bf16 v[36:39], v[44:47], v[224:227], v[36:39]
	v_mfma_f32_16x16x32_bf16 v[72:75], v[44:47], v[200:203], v[72:75]
	v_mfma_f32_16x16x32_bf16 v[68:71], v[76:79], v[200:203], v[68:71]
	v_mfma_f32_16x16x32_bf16 v[64:67], v[44:47], v[208:211], v[64:67]
	v_mfma_f32_16x16x32_bf16 v[60:63], v[76:79], v[208:211], v[60:63]
	v_mfma_f32_16x16x32_bf16 v[56:59], v[44:47], v[216:219], v[56:59]
	v_mfma_f32_16x16x32_bf16 v[52:55], v[76:79], v[216:219], v[52:55]
	v_mfma_f32_16x16x32_bf16 v[92:95], v[48:51], v[228:231], v[36:39]
	v_mfma_f32_16x16x32_bf16 v[36:39], v[76:79], v[224:227], v[40:43]
	v_mfma_f32_16x16x32_bf16 v[72:75], v[48:51], v[204:207], v[72:75]
	v_mfma_f32_16x16x32_bf16 v[68:71], v[80:83], v[204:207], v[68:71]
	v_mfma_f32_16x16x32_bf16 v[64:67], v[48:51], v[212:215], v[64:67]
	v_mfma_f32_16x16x32_bf16 v[60:63], v[80:83], v[212:215], v[60:63]
	v_mfma_f32_16x16x32_bf16 v[56:59], v[48:51], v[220:223], v[56:59]
	v_mfma_f32_16x16x32_bf16 v[52:55], v[80:83], v[220:223], v[52:55]
	v_mfma_f32_16x16x32_bf16 v[88:91], v[80:83], v[228:231], v[36:39]
	v_mfma_f32_16x16x32_bf16 v[32:35], v[84:87], v[200:203], v[32:35]
	v_mfma_f32_16x16x32_bf16 v[28:31], v[164:167], v[200:203], v[28:31]
	v_mfma_f32_16x16x32_bf16 v[24:27], v[84:87], v[208:211], v[24:27]
	v_mfma_f32_16x16x32_bf16 v[20:23], v[164:167], v[208:211], v[20:23]
	v_mfma_f32_16x16x32_bf16 v[16:19], v[84:87], v[216:219], v[16:19]
	v_mfma_f32_16x16x32_bf16 v[12:15], v[164:167], v[216:219], v[12:15]
	v_mfma_f32_16x16x32_bf16 v[8:11], v[84:87], v[224:227], v[8:11]
	v_mfma_f32_16x16x32_bf16 v[4:7], v[164:167], v[224:227], v[4:7]
	v_mfma_f32_16x16x32_bf16 v[32:35], v[96:99], v[204:207], v[32:35]
	v_mfma_f32_16x16x32_bf16 v[28:31], v[168:171], v[204:207], v[28:31]
	v_mfma_f32_16x16x32_bf16 v[24:27], v[96:99], v[212:215], v[24:27]
	v_mfma_f32_16x16x32_bf16 v[20:23], v[168:171], v[212:215], v[20:23]
	v_mfma_f32_16x16x32_bf16 v[16:19], v[96:99], v[220:223], v[16:19]
	v_mfma_f32_16x16x32_bf16 v[12:15], v[168:171], v[220:223], v[12:15]
	v_mfma_f32_16x16x32_bf16 v[8:11], v[96:99], v[228:231], v[8:11]
	v_mfma_f32_16x16x32_bf16 v[4:7], v[168:171], v[228:231], v[4:7]
	s_barrier
	s_add_i32 s45, s45, 2
	s_add_u32 s43, s43, 0x100
	s_addc_u32 s44, s44, 0
	s_add_u32 s0, s0, 0x100
	s_addc_u32 s1, s1, 0
	s_cmp_gt_u32 s45, 29
	s_cbranch_scc0 .LBB0_660
	s_and_b64 vcc, exec, s[52:53]
	s_cbranch_vccz .LBB0_663
	s_barrier

; #define PG8_STAGE(bufoff, gbase, voff) do { _Pragma("unroll") for (int _i = 0; _i < 2; ++_i) \
;         __builtin_amdgcn_global_load_lds((const unsigned*)((const char*)(gbase) + (voff)[_i]), (PG8_LAS unsigned*)(lds + (bufoff) + ldsw + _i * 8192), 16, 0, 0); } while (0)
; #define PG8_LDA(dst, b, h) do { _Pragma("unroll") for (int m = 0; m < 4; ++m) _Pragma("unroll") for (int k = 0; k < 2; ++k) dst[m][k] = *(const PG8_LAS bf16x8*)(lds + PG8_SA(b, h) + aoff + m * 2048 + k * 1024); } while (0)
; #define PG8_LDB(dst, b, h) do { _Pragma("unroll") for (int n = 0; n < 2; ++n) _Pragma("unroll") for (int k = 0; k < 2; ++k) dst[n][k] = *(const PG8_LAS bf16x8*)(lds + PG8_SB(b, h) + boff + n * 2048 + k * 1024); } while (0)
; #define PG8_MMA(ai, bj, At, Bt) do { __builtin_amdgcn_s_setprio(1); _Pragma("unroll") for (int m = 0; m < 4; ++m) _Pragma("unroll") for (int n = 0; n < 2; ++n) _Pragma("unroll") for (int k = 0; k < 2; ++k) \
;         acc[ai][bj][m][n] = __builtin_amdgcn_mfma_f32_16x16x32_bf16(Bt[n][k], At[m][k], acc[ai][bj][m][n], 0, 0, 0); __builtin_amdgcn_s_setprio(0); } while (0)
; #define PG8_WAIT_V(n) asm volatile("s_waitcnt vmcnt(" #n ")" ::: "memory")
; #define PG8_WAIT_L(n) asm volatile("s_waitcnt lgkmcnt(" #n ")" ::: "memory")
; #define PG8_BAR __builtin_amdgcn_s_barrier()
; template <class Epi, class Sched, bool ALIGN_EPI = false, bool SP2 = false>
; __device__ __forceinline__ void gemm_phase(PG8_LAS unsigned char* lds, const Gemm g, const Sched& S, const Epi& E) {
;     ...
;             const char* a1 = cA + (size_t)(t + 1) * kstep;
;             const char* a2 = last ? nA : cA + (size_t)(t + 2) * kstep; const char* b2 = last ? nB : cB + (size_t)(t + 2) * kstep;
;             const char* a3 = a2 + kstep; const char* b3 = b2 + kstep;
;             if (last && has_next) S.a_ready(nxt);
;             if constexpr (SP2) {
;             PG8_LDB(B0, 0, 0); PG8_LDB(B1, 0, 1); PG8_SCHED; PG8_LDA(At, 0, 0); PG8_STAGE(PG8_SA(1, 1), a1 + hstep, voffA);
;             PG8_WAIT_V(8); PG8_WAIT_L(0); PG8_BAR; PG8_MMA(0, 0, At, B0); PG8_MMA(0, 1, At, B1); PG8_BAR; PG8_SCHED;
;             PG8_LDA(At, 0, 1); PG8_STAGE(PG8_SB(0, 0), b2, voffB); PG8_STAGE(PG8_SB(0, 1), b2 + hstep, voffB); PG8_STAGE(PG8_SA(0, 0), a2, voffA);
;             PG8_WAIT_V(8); PG8_WAIT_L(0); PG8_BAR; PG8_MMA(1, 0, At, B0); PG8_MMA(1, 1, At, B1); PG8_BAR; PG8_SCHED;
.Lprio_done_822:
.LBB0_822:
	s_add_u32 s14, s0, 0x100
	s_addc_u32 s15, s1, 0
	s_add_i32 s60, 0, 0x10000
	s_cmpk_eq_i32 s25, 0x52
	s_cselect_b32 s19, s41, s15
	s_cselect_b32 s18, s40, s14
	s_cselect_b32 s17, s51, s24
	s_cselect_b32 s16, s50, s23
	s_add_i32 s61, 0, 0x14000
	v_add_u32_e32 v154, s60, v159
	v_add_u32_e32 v170, s61, v159
	ds_read_b128 v[116:119], v154
	ds_read_b128 v[120:123], v154 offset:1024
	ds_read_b128 v[150:153], v154 offset:2048
	ds_read_b128 v[154:157], v154 offset:3072
	ds_read_b128 v[162:165], v170
	ds_read_b128 v[166:169], v170 offset:1024
	ds_read_b128 v[184:187], v170 offset:2048
	ds_read_b128 v[188:191], v170 offset:3072
	v_lshl_add_u64 v[170:171], s[0:1], 0, v[148:149]
	s_add_i32 m0, s31, 0xc000
	ds_read_b128 v[192:195], v161
	ds_read_b128 v[196:199], v161 offset:1024
	ds_read_b128 v[200:203], v161 offset:2048
	ds_read_b128 v[204:207], v161 offset:3072
	ds_read_b128 v[208:211], v161 offset:4096
	ds_read_b128 v[212:215], v161 offset:5120
	ds_read_b128 v[216:219], v161 offset:6144
	ds_read_b128 v[220:223], v161 offset:7168
	global_load_lds_dwordx4 v[170:171], off
	v_lshl_add_u64 v[170:171], s[0:1], 0, v[146:147]
	s_add_i32 m0, s31, 0xe000
	s_nop 0
	global_load_lds_dwordx4 v[170:171], off
	s_waitcnt vmcnt(8)
	s_waitcnt lgkmcnt(0)
	s_barrier
	s_waitcnt lgkmcnt(0)
	v_mfma_f32_16x16x32_bf16 v[136:139], v[116:119], v[192:195], v[136:139]
	v_mfma_f32_16x16x32_bf16 v[132:135], v[150:153], v[192:195], v[132:135]
	v_mfma_f32_16x16x32_bf16 v[112:115], v[116:119], v[200:203], v[112:115]
	v_mfma_f32_16x16x32_bf16 v[108:111], v[150:153], v[200:203], v[108:111]
	v_mfma_f32_16x16x32_bf16 v[96:99], v[116:119], v[208:211], v[96:99]
	v_mfma_f32_16x16x32_bf16 v[92:95], v[150:153], v[208:211], v[92:95]
	v_mfma_f32_16x16x32_bf16 v[80:83], v[116:119], v[216:219], v[80:83]
	v_mfma_f32_16x16x32_bf16 v[76:79], v[150:153], v[216:219], v[76:79]
	v_mfma_f32_16x16x32_bf16 v[136:139], v[120:123], v[196:199], v[136:139]
	v_mfma_f32_16x16x32_bf16 v[132:135], v[154:157], v[196:199], v[132:135]
	v_mfma_f32_16x16x32_bf16 v[112:115], v[120:123], v[204:207], v[112:115]
	v_mfma_f32_16x16x32_bf16 v[108:111], v[154:157], v[204:207], v[108:111]
	v_mfma_f32_16x16x32_bf16 v[96:99], v[120:123], v[212:215], v[96:99]
	v_mfma_f32_16x16x32_bf16 v[92:95], v[154:157], v[212:215], v[92:95]
	v_mfma_f32_16x16x32_bf16 v[80:83], v[120:123], v[220:223], v[80:83]
	v_mfma_f32_16x16x32_bf16 v[76:79], v[154:157], v[220:223], v[76:79]
	v_mfma_f32_16x16x32_bf16 v[128:131], v[162:165], v[192:195], v[128:131]
	v_mfma_f32_16x16x32_bf16 v[124:127], v[184:187], v[192:195], v[124:127]
	v_mfma_f32_16x16x32_bf16 v[104:107], v[162:165], v[200:203], v[104:107]
	v_mfma_f32_16x16x32_bf16 v[100:103], v[184:187], v[200:203], v[100:103]
	v_mfma_f32_16x16x32_bf16 v[88:91], v[162:165], v[208:211], v[88:91]
	v_mfma_f32_16x16x32_bf16 v[84:87], v[184:187], v[208:211], v[84:87]
	v_mfma_f32_16x16x32_bf16 v[72:75], v[162:165], v[216:219], v[72:75]
	v_mfma_f32_16x16x32_bf16 v[68:71], v[184:187], v[216:219], v[68:71]
	v_mfma_f32_16x16x32_bf16 v[128:131], v[166:169], v[196:199], v[128:131]
	v_mfma_f32_16x16x32_bf16 v[124:127], v[188:191], v[196:199], v[124:127]
	v_mfma_f32_16x16x32_bf16 v[104:107], v[166:169], v[204:207], v[104:107]
	v_mfma_f32_16x16x32_bf16 v[100:103], v[188:191], v[204:207], v[100:103]
	v_mfma_f32_16x16x32_bf16 v[88:91], v[166:169], v[212:215], v[88:91]
	v_mfma_f32_16x16x32_bf16 v[84:87], v[188:191], v[212:215], v[84:87]
	v_mfma_f32_16x16x32_bf16 v[72:75], v[166:169], v[220:223], v[72:75]
	v_mfma_f32_16x16x32_bf16 v[68:71], v[188:191], v[220:223], v[68:71]
	s_barrier
	s_add_i32 s0, s60, s30
	v_lshl_add_u64 v[170:171], s[16:17], 0, v[174:175]
	s_mov_b32 m0, s0
	global_load_lds_dwordx4 v[170:171], off
	s_add_i32 m0, s0, 0x2000
	s_add_u32 s0, s16, 0x158000
	v_lshl_add_u64 v[224:225], s[16:17], 0, v[140:141]
	s_addc_u32 s1, s17, 0
	s_add_i32 s60, s61, s30
	global_load_lds_dwordx4 v[224:225], off
	v_lshl_add_u64 v[226:227], s[0:1], 0, v[174:175]
	s_mov_b32 m0, s60
	v_lshl_add_u64 v[228:229], s[18:19], 0, v[142:143]
	global_load_lds_dwordx4 v[226:227], off
	v_lshl_add_u64 v[226:227], s[0:1], 0, v[140:141]
	s_add_i32 m0, s60, 0x2000
	s_nop 0
	global_load_lds_dwordx4 v[226:227], off
	v_lshl_add_u64 v[226:227], s[18:19], 0, v[144:145]
	s_mov_b32 m0, s31
	s_nop 0
	global_load_lds_dwordx4 v[226:227], off
	s_mov_b32 m0, s34
	s_nop 0
	global_load_lds_dwordx4 v[228:229], off
	ds_read_b128 v[192:195], v161 offset:16384
	ds_read_b128 v[196:199], v161 offset:17408
	ds_read_b128 v[200:203], v161 offset:18432
	ds_read_b128 v[204:207], v161 offset:19456
	ds_read_b128 v[208:211], v161 offset:20480
	ds_read_b128 v[212:215], v161 offset:21504
	ds_read_b128 v[216:219], v161 offset:22528
	ds_read_b128 v[220:223], v161 offset:23552
	s_waitcnt vmcnt(8)
	s_waitcnt lgkmcnt(0)
	s_barrier
; #define PG8_STAGE(bufoff, gbase, voff) do { _Pragma("unroll") for (int _i = 0; _i < 2; ++_i) \
;         __builtin_amdgcn_global_load_lds((const unsigned*)((const char*)(gbase) + (voff)[_i]), (PG8_LAS unsigned*)(lds + (bufoff) + ldsw + _i * 8192), 16, 0, 0); } while (0)
; #define PG8_LDA(dst, b, h) do { _Pragma("unroll") for (int m = 0; m < 4; ++m) _Pragma("unroll") for (int k = 0; k < 2; ++k) dst[m][k] = *(const PG8_LAS bf16x8*)(lds + PG8_SA(b, h) + aoff + m * 2048 + k * 1024); } while (0)
; #define PG8_LDB(dst, b, h) do { _Pragma("unroll") for (int n = 0; n < 2; ++n) _Pragma("unroll") for (int k = 0; k < 2; ++k) dst[n][k] = *(const PG8_LAS bf16x8*)(lds + PG8_SB(b, h) + boff + n * 2048 + k * 1024); } while (0)
; #define PG8_MMA(ai, bj, At, Bt) do { __builtin_amdgcn_s_setprio(1); _Pragma("unroll") for (int m = 0; m < 4; ++m) _Pragma("unroll") for (int n = 0; n < 2; ++n) _Pragma("unroll") for (int k = 0; k < 2; ++k) \
;         acc[ai][bj][m][n] = __builtin_amdgcn_mfma_f32_16x16x32_bf16(Bt[n][k], At[m][k], acc[ai][bj][m][n], 0, 0, 0); __builtin_amdgcn_s_setprio(0); } while (0)
; #define PG8_WAIT_V(n) asm volatile("s_waitcnt vmcnt(" #n ")" ::: "memory")
; #define PG8_WAIT_L(n) asm volatile("s_waitcnt lgkmcnt(" #n ")" ::: "memory")
; #define PG8_BAR __builtin_amdgcn_s_barrier()
; #define PG8_SCHED __builtin_amdgcn_sched_barrier(0)
; template <class Epi, class Sched, bool ALIGN_EPI = false, bool SP2 = false>
; __device__ __forceinline__ void gemm_phase(PG8_LAS unsigned char* lds, const Gemm g, const Sched& S, const Epi& E) {
;     ...
;             PG8_LDA(At, 0, 1); PG8_STAGE(PG8_SB(0, 0), b2, voffB); PG8_STAGE(PG8_SB(0, 1), b2 + hstep, voffB); PG8_STAGE(PG8_SA(0, 0), a2, voffA);
;             PG8_WAIT_V(8); PG8_WAIT_L(0); PG8_BAR; PG8_MMA(1, 0, At, B0); PG8_MMA(1, 1, At, B1); PG8_BAR; PG8_SCHED;
;             PG8_LDB(B0, 1, 0); PG8_LDB(B1, 1, 1); PG8_SCHED; PG8_LDA(At, 1, 0); PG8_STAGE(PG8_SA(0, 1), a2 + hstep, voffA);
;             PG8_WAIT_V(8); PG8_WAIT_L(0); PG8_BAR; PG8_MMA(0, 0, At, B0); PG8_MMA(0, 1, At, B1); PG8_BAR; PG8_SCHED;
	s_waitcnt lgkmcnt(0)
	v_mfma_f32_16x16x32_bf16 v[64:67], v[116:119], v[192:195], v[64:67]
	v_mfma_f32_16x16x32_bf16 v[60:63], v[150:153], v[192:195], v[60:63]
	v_mfma_f32_16x16x32_bf16 v[48:51], v[116:119], v[200:203], v[48:51]
	v_mfma_f32_16x16x32_bf16 v[44:47], v[150:153], v[200:203], v[44:47]
	v_mfma_f32_16x16x32_bf16 v[32:35], v[116:119], v[208:211], v[32:35]
	v_mfma_f32_16x16x32_bf16 v[28:31], v[150:153], v[208:211], v[28:31]
	v_mfma_f32_16x16x32_bf16 v[16:19], v[116:119], v[216:219], v[16:19]
	v_mfma_f32_16x16x32_bf16 v[12:15], v[150:153], v[216:219], v[12:15]
	v_mfma_f32_16x16x32_bf16 v[64:67], v[120:123], v[196:199], v[64:67]
	v_mfma_f32_16x16x32_bf16 v[60:63], v[154:157], v[196:199], v[60:63]
	v_mfma_f32_16x16x32_bf16 v[48:51], v[120:123], v[204:207], v[48:51]
	v_mfma_f32_16x16x32_bf16 v[44:47], v[154:157], v[204:207], v[44:47]
	v_mfma_f32_16x16x32_bf16 v[32:35], v[120:123], v[212:215], v[32:35]
	v_mfma_f32_16x16x32_bf16 v[28:31], v[154:157], v[212:215], v[28:31]
	v_mfma_f32_16x16x32_bf16 v[16:19], v[120:123], v[220:223], v[16:19]
	v_mfma_f32_16x16x32_bf16 v[12:15], v[154:157], v[220:223], v[12:15]
	v_mfma_f32_16x16x32_bf16 v[56:59], v[162:165], v[192:195], v[56:59]
	v_mfma_f32_16x16x32_bf16 v[52:55], v[184:187], v[192:195], v[52:55]
	v_mfma_f32_16x16x32_bf16 v[40:43], v[162:165], v[200:203], v[40:43]
	v_mfma_f32_16x16x32_bf16 v[36:39], v[184:187], v[200:203], v[36:39]
	v_mfma_f32_16x16x32_bf16 v[24:27], v[162:165], v[208:211], v[24:27]
	v_mfma_f32_16x16x32_bf16 v[20:23], v[184:187], v[208:211], v[20:23]
	v_mfma_f32_16x16x32_bf16 v[8:11], v[162:165], v[216:219], v[8:11]
	v_mfma_f32_16x16x32_bf16 v[4:7], v[184:187], v[216:219], v[4:7]
	v_mfma_f32_16x16x32_bf16 v[56:59], v[166:169], v[196:199], v[56:59]
	v_mfma_f32_16x16x32_bf16 v[52:55], v[188:191], v[196:199], v[52:55]
	v_mfma_f32_16x16x32_bf16 v[40:43], v[166:169], v[204:207], v[40:43]
	v_mfma_f32_16x16x32_bf16 v[36:39], v[188:191], v[204:207], v[36:39]
	v_mfma_f32_16x16x32_bf16 v[24:27], v[166:169], v[212:215], v[24:27]
	v_mfma_f32_16x16x32_bf16 v[20:23], v[188:191], v[212:215], v[20:23]
	v_mfma_f32_16x16x32_bf16 v[8:11], v[166:169], v[220:223], v[8:11]
	v_mfma_f32_16x16x32_bf16 v[4:7], v[188:191], v[220:223], v[4:7]
	s_barrier
	s_add_i32 s60, 0, 0x18000
	s_add_i32 s61, 0, 0x1c000
	v_add_u32_e32 v154, s60, v159
	v_add_u32_e32 v179, s61, v159
	ds_read_b128 v[116:119], v154
	ds_read_b128 v[120:123], v154 offset:1024
	ds_read_b128 v[150:153], v154 offset:2048
	ds_read_b128 v[154:157], v154 offset:3072
	ds_read_b128 v[162:165], v179
	ds_read_b128 v[166:169], v179 offset:1024
	ds_read_b128 v[184:187], v179 offset:2048
	ds_read_b128 v[188:191], v179 offset:3072
	s_add_u32 s0, s18, 0x158000
	s_addc_u32 s1, s19, 0
	s_mov_b32 m0, s35
	v_lshl_add_u64 v[230:231], s[0:1], 0, v[144:145]
	ds_read_b128 v[192:195], v161 offset:32768
	ds_read_b128 v[196:199], v161 offset:33792
	ds_read_b128 v[200:203], v161 offset:34816
	ds_read_b128 v[204:207], v161 offset:35840
	ds_read_b128 v[208:211], v161 offset:36864
	ds_read_b128 v[212:215], v161 offset:37888
	ds_read_b128 v[216:219], v161 offset:38912
	ds_read_b128 v[220:223], v161 offset:39936
	global_load_lds_dwordx4 v[230:231], off
	v_lshl_add_u64 v[230:231], s[0:1], 0, v[142:143]
	s_mov_b32 m0, s52
	s_nop 0
	global_load_lds_dwordx4 v[230:231], off
	s_waitcnt vmcnt(8)
	s_waitcnt lgkmcnt(0)
	s_barrier
	s_waitcnt lgkmcnt(0)
	v_mfma_f32_16x16x32_bf16 v[136:139], v[116:119], v[192:195], v[136:139]
	v_mfma_f32_16x16x32_bf16 v[132:135], v[150:153], v[192:195], v[132:135]
	v_mfma_f32_16x16x32_bf16 v[112:115], v[116:119], v[200:203], v[112:115]
	v_mfma_f32_16x16x32_bf16 v[108:111], v[150:153], v[200:203], v[108:111]
	v_mfma_f32_16x16x32_bf16 v[96:99], v[116:119], v[208:211], v[96:99]
	v_mfma_f32_16x16x32_bf16 v[92:95], v[150:153], v[208:211], v[92:95]
	v_mfma_f32_16x16x32_bf16 v[80:83], v[116:119], v[216:219], v[80:83]
	v_mfma_f32_16x16x32_bf16 v[76:79], v[150:153], v[216:219], v[76:79]
	v_mfma_f32_16x16x32_bf16 v[136:139], v[120:123], v[196:199], v[136:139]
	v_mfma_f32_16x16x32_bf16 v[132:135], v[154:157], v[196:199], v[132:135]
	v_mfma_f32_16x16x32_bf16 v[112:115], v[120:123], v[204:207], v[112:115]
	v_mfma_f32_16x16x32_bf16 v[108:111], v[154:157], v[204:207], v[108:111]
	v_mfma_f32_16x16x32_bf16 v[96:99], v[120:123], v[212:215], v[96:99]
	v_mfma_f32_16x16x32_bf16 v[92:95], v[154:157], v[212:215], v[92:95]
	v_mfma_f32_16x16x32_bf16 v[80:83], v[120:123], v[220:223], v[80:83]
	v_mfma_f32_16x16x32_bf16 v[76:79], v[154:157], v[220:223], v[76:79]
	v_mfma_f32_16x16x32_bf16 v[128:131], v[162:165], v[192:195], v[128:131]
	v_mfma_f32_16x16x32_bf16 v[124:127], v[184:187], v[192:195], v[124:127]
	v_mfma_f32_16x16x32_bf16 v[104:107], v[162:165], v[200:203], v[104:107]
	v_mfma_f32_16x16x32_bf16 v[100:103], v[184:187], v[200:203], v[100:103]
	v_mfma_f32_16x16x32_bf16 v[88:91], v[162:165], v[208:211], v[88:91]
	v_mfma_f32_16x16x32_bf16 v[84:87], v[184:187], v[208:211], v[84:87]
	v_mfma_f32_16x16x32_bf16 v[72:75], v[162:165], v[216:219], v[72:75]
	v_mfma_f32_16x16x32_bf16 v[68:71], v[184:187], v[216:219], v[68:71]
	v_mfma_f32_16x16x32_bf16 v[128:131], v[166:169], v[196:199], v[128:131]
	v_mfma_f32_16x16x32_bf16 v[124:127], v[188:191], v[196:199], v[124:127]
	v_mfma_f32_16x16x32_bf16 v[104:107], v[166:169], v[204:207], v[104:107]
	v_mfma_f32_16x16x32_bf16 v[100:103], v[188:191], v[204:207], v[100:103]
	v_mfma_f32_16x16x32_bf16 v[88:91], v[166:169], v[212:215], v[88:91]
	v_mfma_f32_16x16x32_bf16 v[84:87], v[188:191], v[212:215], v[84:87]
	v_mfma_f32_16x16x32_bf16 v[72:75], v[166:169], v[220:223], v[72:75]
	v_mfma_f32_16x16x32_bf16 v[68:71], v[188:191], v[220:223], v[68:71]
	s_barrier
; #define PG8_STAGE(bufoff, gbase, voff) do { _Pragma("unroll") for (int _i = 0; _i < 2; ++_i) \
;         __builtin_amdgcn_global_load_lds((const unsigned*)((const char*)(gbase) + (voff)[_i]), (PG8_LAS unsigned*)(lds + (bufoff) + ldsw + _i * 8192), 16, 0, 0); } while (0)
; #define PG8_LDA(dst, b, h) do { _Pragma("unroll") for (int m = 0; m < 4; ++m) _Pragma("unroll") for (int k = 0; k < 2; ++k) dst[m][k] = *(const PG8_LAS bf16x8*)(lds + PG8_SA(b, h) + aoff + m * 2048 + k * 1024); } while (0)
; #define PG8_MMA(ai, bj, At, Bt) do { __builtin_amdgcn_s_setprio(1); _Pragma("unroll") for (int m = 0; m < 4; ++m) _Pragma("unroll") for (int n = 0; n < 2; ++n) _Pragma("unroll") for (int k = 0; k < 2; ++k) \
;         acc[ai][bj][m][n] = __builtin_amdgcn_mfma_f32_16x16x32_bf16(Bt[n][k], At[m][k], acc[ai][bj][m][n], 0, 0, 0); __builtin_amdgcn_s_setprio(0); } while (0)
; #define PG8_WAIT_V(n) asm volatile("s_waitcnt vmcnt(" #n ")" ::: "memory")
; #define PG8_WAIT_L(n) asm volatile("s_waitcnt lgkmcnt(" #n ")" ::: "memory")
; #define PG8_BAR __builtin_amdgcn_s_barrier()
; #define PG8_SCHED __builtin_amdgcn_sched_barrier(0)
; template <class Epi, class Sched, bool ALIGN_EPI = false, bool SP2 = false>
; __device__ __forceinline__ void gemm_phase(PG8_LAS unsigned char* lds, const Gemm g, const Sched& S, const Epi& E) {
;     ...
;         for (int t = 0; t < nt; t += 2) {
;             const bool last = (t == nt - 2);
;     ...
;             PG8_LDA(At, 1, 1); PG8_STAGE(PG8_SB(1, 0), b3, voffB); PG8_STAGE(PG8_SB(1, 1), b3 + hstep, voffB); PG8_STAGE(PG8_SA(1, 0), a3, voffA);
;             PG8_WAIT_V(8); PG8_WAIT_L(0); PG8_BAR; PG8_MMA(1, 0, At, B0); PG8_MMA(1, 1, At, B1); PG8_BAR; PG8_SCHED;
	s_add_i32 s0, s60, s30
	v_lshl_add_u64 v[170:171], v[170:171], 0, s[10:11]
	s_mov_b32 m0, s0
	global_load_lds_dwordx4 v[170:171], off
	s_add_i32 m0, s0, 0x2000
	s_add_u32 s0, s16, 0x158080
	v_lshl_add_u64 v[170:171], v[224:225], 0, s[10:11]
	s_addc_u32 s1, s17, 0
	s_add_i32 s16, s61, s30
	global_load_lds_dwordx4 v[170:171], off
	v_lshl_add_u64 v[170:171], s[0:1], 0, v[174:175]
	s_mov_b32 m0, s16
	s_nop 0
	global_load_lds_dwordx4 v[170:171], off
	v_lshl_add_u64 v[170:171], s[0:1], 0, v[140:141]
	s_add_i32 m0, s16, 0x2000
	s_nop 0
	global_load_lds_dwordx4 v[170:171], off
	v_lshl_add_u64 v[170:171], v[226:227], 0, s[10:11]
	s_mov_b32 m0, s54
	s_nop 0
	global_load_lds_dwordx4 v[170:171], off
	v_lshl_add_u64 v[170:171], v[228:229], 0, s[10:11]
	s_mov_b32 m0, s55
	s_nop 0
	global_load_lds_dwordx4 v[170:171], off
	ds_read_b128 v[192:195], v161 offset:49152
	ds_read_b128 v[196:199], v161 offset:50176
	ds_read_b128 v[200:203], v161 offset:51200
	ds_read_b128 v[204:207], v161 offset:52224
	ds_read_b128 v[208:211], v161 offset:53248
	ds_read_b128 v[212:215], v161 offset:54272
	ds_read_b128 v[216:219], v161 offset:55296
	ds_read_b128 v[220:223], v161 offset:56320
	s_waitcnt vmcnt(8)
	s_waitcnt lgkmcnt(0)
	s_barrier
	s_waitcnt lgkmcnt(0)
	v_mfma_f32_16x16x32_bf16 v[64:67], v[116:119], v[192:195], v[64:67]
	v_mfma_f32_16x16x32_bf16 v[60:63], v[150:153], v[192:195], v[60:63]
	v_mfma_f32_16x16x32_bf16 v[48:51], v[116:119], v[200:203], v[48:51]
	v_mfma_f32_16x16x32_bf16 v[44:47], v[150:153], v[200:203], v[44:47]
	v_mfma_f32_16x16x32_bf16 v[32:35], v[116:119], v[208:211], v[32:35]
	v_mfma_f32_16x16x32_bf16 v[28:31], v[150:153], v[208:211], v[28:31]
	v_mfma_f32_16x16x32_bf16 v[16:19], v[116:119], v[216:219], v[16:19]
	v_mfma_f32_16x16x32_bf16 v[12:15], v[150:153], v[216:219], v[12:15]
	v_mfma_f32_16x16x32_bf16 v[64:67], v[120:123], v[196:199], v[64:67]
	v_mfma_f32_16x16x32_bf16 v[60:63], v[154:157], v[196:199], v[60:63]
	v_mfma_f32_16x16x32_bf16 v[48:51], v[120:123], v[204:207], v[48:51]
	v_mfma_f32_16x16x32_bf16 v[44:47], v[154:157], v[204:207], v[44:47]
	v_mfma_f32_16x16x32_bf16 v[32:35], v[120:123], v[212:215], v[32:35]
	v_mfma_f32_16x16x32_bf16 v[28:31], v[154:157], v[212:215], v[28:31]
	v_mfma_f32_16x16x32_bf16 v[16:19], v[120:123], v[220:223], v[16:19]
	v_mfma_f32_16x16x32_bf16 v[12:15], v[154:157], v[220:223], v[12:15]
	v_mfma_f32_16x16x32_bf16 v[56:59], v[162:165], v[192:195], v[56:59]
	v_mfma_f32_16x16x32_bf16 v[52:55], v[184:187], v[192:195], v[52:55]
	v_mfma_f32_16x16x32_bf16 v[40:43], v[162:165], v[200:203], v[40:43]
	v_mfma_f32_16x16x32_bf16 v[36:39], v[184:187], v[200:203], v[36:39]
	v_mfma_f32_16x16x32_bf16 v[24:27], v[162:165], v[208:211], v[24:27]
	v_mfma_f32_16x16x32_bf16 v[20:23], v[184:187], v[208:211], v[20:23]
	v_mfma_f32_16x16x32_bf16 v[8:11], v[162:165], v[216:219], v[8:11]
	v_mfma_f32_16x16x32_bf16 v[4:7], v[184:187], v[216:219], v[4:7]
	v_mfma_f32_16x16x32_bf16 v[56:59], v[166:169], v[196:199], v[56:59]
	v_mfma_f32_16x16x32_bf16 v[52:55], v[188:191], v[196:199], v[52:55]
	v_mfma_f32_16x16x32_bf16 v[40:43], v[166:169], v[204:207], v[40:43]
	v_mfma_f32_16x16x32_bf16 v[36:39], v[188:191], v[204:207], v[36:39]
	v_mfma_f32_16x16x32_bf16 v[24:27], v[166:169], v[212:215], v[24:27]
	v_mfma_f32_16x16x32_bf16 v[20:23], v[188:191], v[212:215], v[20:23]
	v_mfma_f32_16x16x32_bf16 v[8:11], v[166:169], v[220:223], v[8:11]
	v_mfma_f32_16x16x32_bf16 v[4:7], v[188:191], v[220:223], v[4:7]
	s_barrier
	s_add_i32 s25, s25, 2
	s_add_u32 s23, s23, 0x100
	s_addc_u32 s24, s24, 0
	s_cmpk_gt_u32 s25, 0x53
	s_mov_b64 s[0:1], s[14:15]
	s_cbranch_scc0 .LBB0_822
	s_and_b64 vcc, exec, s[48:49]
	s_cbranch_vccz .LBB0_825
	s_barrier
